# GEMM phases: adjacent s_waitcnt vmcnt(N) and s_waitcnt lgkmcnt(0) fused into one instruction (24 sites), on top of v79
# speedup vs baseline: 1.0001x; 1.0001x over previous
.LBB0_173:
	s_waitcnt lgkmcnt(0)
	ds_read_b128 v[148:151], v172
	ds_read_b128 v[152:155], v172 offset:1024
	ds_read_b128 v[156:159], v172 offset:2048
	ds_read_b128 v[160:163], v172 offset:3072
	ds_read_b128 v[178:181], v173
	ds_read_b128 v[182:185], v173 offset:1024
	ds_read_b128 v[186:189], v173 offset:2048
	ds_read_b128 v[190:193], v173 offset:3072
	s_add_u32 s7, s80, 0xfffc0080
	s_addc_u32 s24, s81, -1
	s_cmp_eq_u32 s6, 12
	s_cselect_b32 s85, s1, s24
	s_cselect_b32 s84, s75, s7
	s_cselect_b32 s83, s73, s33
	s_cselect_b32 s82, vcc_lo, vcc_hi
	v_lshl_add_u64 v[198:199], s[80:81], 0, v[140:141]
	s_add_i32 m0, s65, 0xc000
	ds_read_b128 v[194:197], v174
	ds_read_b128 v[202:205], v174 offset:1024
	ds_read_b128 v[210:213], v174 offset:2048
	ds_read_b128 v[214:217], v174 offset:3072
	ds_read_b128 v[218:221], v174 offset:4096
	ds_read_b128 v[222:225], v174 offset:5120
	ds_read_b128 v[226:229], v174 offset:6144
	ds_read_b128 v[230:233], v174 offset:7168
	global_load_lds_dwordx4 v[198:199], off
	v_lshl_add_u64 v[198:199], s[80:81], 0, v[142:143]
	s_add_i32 m0, s65, 0xe000
	s_nop 0
	global_load_lds_dwordx4 v[198:199], off
	s_waitcnt vmcnt(8) lgkmcnt(0)
	s_barrier
	s_setprio 1
	v_mfma_f32_16x16x32_bf16 v[124:127], v[148:151], v[194:197], v[124:127]
	v_mfma_f32_16x16x32_bf16 v[120:123], v[156:159], v[194:197], v[120:123]
	v_mfma_f32_16x16x32_bf16 v[112:115], v[148:151], v[210:213], v[112:115]
	v_mfma_f32_16x16x32_bf16 v[104:107], v[156:159], v[210:213], v[104:107]
	v_mfma_f32_16x16x32_bf16 v[100:103], v[148:151], v[218:221], v[100:103]
	v_mfma_f32_16x16x32_bf16 v[92:95], v[156:159], v[218:221], v[92:95]
	v_mfma_f32_16x16x32_bf16 v[84:87], v[148:151], v[226:229], v[84:87]
	v_mfma_f32_16x16x32_bf16 v[76:79], v[156:159], v[226:229], v[76:79]
	v_mfma_f32_16x16x32_bf16 v[124:127], v[152:155], v[202:205], v[124:127]
	v_mfma_f32_16x16x32_bf16 v[120:123], v[160:163], v[202:205], v[120:123]
	v_mfma_f32_16x16x32_bf16 v[112:115], v[152:155], v[214:217], v[112:115]
	v_mfma_f32_16x16x32_bf16 v[104:107], v[160:163], v[214:217], v[104:107]
	v_mfma_f32_16x16x32_bf16 v[100:103], v[152:155], v[222:225], v[100:103]
	v_mfma_f32_16x16x32_bf16 v[92:95], v[160:163], v[222:225], v[92:95]
	v_mfma_f32_16x16x32_bf16 v[84:87], v[152:155], v[230:233], v[84:87]
	v_mfma_f32_16x16x32_bf16 v[76:79], v[160:163], v[230:233], v[76:79]
	v_mfma_f32_16x16x32_bf16 v[116:119], v[178:181], v[194:197], v[116:119]
	v_mfma_f32_16x16x32_bf16 v[108:111], v[186:189], v[194:197], v[108:111]
	v_mfma_f32_16x16x32_bf16 v[96:99], v[178:181], v[210:213], v[96:99]
	v_mfma_f32_16x16x32_bf16 v[88:91], v[186:189], v[210:213], v[88:91]
	v_mfma_f32_16x16x32_bf16 v[80:83], v[178:181], v[218:221], v[80:83]
	v_mfma_f32_16x16x32_bf16 v[72:75], v[186:189], v[218:221], v[72:75]
	v_mfma_f32_16x16x32_bf16 v[68:71], v[178:181], v[226:229], v[68:71]
	v_mfma_f32_16x16x32_bf16 v[64:67], v[186:189], v[226:229], v[64:67]
	v_mfma_f32_16x16x32_bf16 v[116:119], v[182:185], v[202:205], v[116:119]
	v_mfma_f32_16x16x32_bf16 v[108:111], v[190:193], v[202:205], v[108:111]
	v_mfma_f32_16x16x32_bf16 v[96:99], v[182:185], v[214:217], v[96:99]
	v_mfma_f32_16x16x32_bf16 v[88:91], v[190:193], v[214:217], v[88:91]
	v_mfma_f32_16x16x32_bf16 v[80:83], v[182:185], v[222:225], v[80:83]
	v_mfma_f32_16x16x32_bf16 v[72:75], v[190:193], v[222:225], v[72:75]
	v_mfma_f32_16x16x32_bf16 v[68:71], v[182:185], v[230:233], v[68:71]
	v_mfma_f32_16x16x32_bf16 v[64:67], v[190:193], v[230:233], v[64:67]
	s_setprio 0
	s_barrier
	s_add_i32 s7, s95, s13
	v_lshl_add_u64 v[198:199], s[82:83], 0, v[132:133]
	s_mov_b32 m0, s7
	ds_read_b128 v[194:197], v174 offset:16384
	ds_read_b128 v[202:205], v174 offset:17408
	ds_read_b128 v[210:213], v174 offset:18432
	ds_read_b128 v[214:217], v174 offset:19456
	ds_read_b128 v[218:221], v174 offset:20480
	ds_read_b128 v[222:225], v174 offset:21504
	ds_read_b128 v[226:229], v174 offset:22528
	ds_read_b128 v[230:233], v174 offset:23552
	global_load_lds_dwordx4 v[198:199], off
	s_add_i32 m0, s7, 0x2000
	s_add_u32 s24, s82, 0x40000
	v_lshl_add_u64 v[206:207], s[82:83], 0, v[136:137]
	s_addc_u32 s25, s83, 0
	s_add_i32 s7, s96, s13
	global_load_lds_dwordx4 v[206:207], off
	v_lshl_add_u64 v[234:235], s[24:25], 0, v[132:133]
	s_mov_b32 m0, s7
	v_lshl_add_u64 v[236:237], s[84:85], 0, v[134:135]
	global_load_lds_dwordx4 v[234:235], off
	v_lshl_add_u64 v[234:235], s[24:25], 0, v[136:137]
	s_add_i32 m0, s7, 0x2000
	s_nop 0
	global_load_lds_dwordx4 v[234:235], off
	s_waitcnt vmcnt(6) lgkmcnt(0)
	s_barrier
	s_setprio 1
	v_mfma_f32_16x16x32_bf16 v[60:63], v[148:151], v[194:197], v[60:63]
	v_mfma_f32_16x16x32_bf16 v[56:59], v[156:159], v[194:197], v[56:59]
	v_mfma_f32_16x16x32_bf16 v[52:55], v[148:151], v[210:213], v[52:55]
	v_mfma_f32_16x16x32_bf16 v[44:47], v[156:159], v[210:213], v[44:47]
	v_mfma_f32_16x16x32_bf16 v[36:39], v[148:151], v[218:221], v[36:39]
	v_mfma_f32_16x16x32_bf16 v[28:31], v[156:159], v[218:221], v[28:31]
	v_mfma_f32_16x16x32_bf16 v[20:23], v[148:151], v[226:229], v[20:23]
	v_mfma_f32_16x16x32_bf16 v[12:15], v[156:159], v[226:229], v[12:15]
	v_mfma_f32_16x16x32_bf16 v[60:63], v[152:155], v[202:205], v[60:63]
	v_mfma_f32_16x16x32_bf16 v[56:59], v[160:163], v[202:205], v[56:59]
	v_mfma_f32_16x16x32_bf16 v[52:55], v[152:155], v[214:217], v[52:55]
	v_mfma_f32_16x16x32_bf16 v[44:47], v[160:163], v[214:217], v[44:47]
	v_mfma_f32_16x16x32_bf16 v[36:39], v[152:155], v[222:225], v[36:39]
	v_mfma_f32_16x16x32_bf16 v[28:31], v[160:163], v[222:225], v[28:31]
	v_mfma_f32_16x16x32_bf16 v[20:23], v[152:155], v[230:233], v[20:23]
	v_mfma_f32_16x16x32_bf16 v[12:15], v[160:163], v[230:233], v[12:15]
	v_mfma_f32_16x16x32_bf16 v[48:51], v[178:181], v[194:197], v[48:51]
	v_mfma_f32_16x16x32_bf16 v[40:43], v[186:189], v[194:197], v[40:43]
	v_mfma_f32_16x16x32_bf16 v[32:35], v[178:181], v[210:213], v[32:35]
	v_mfma_f32_16x16x32_bf16 v[24:27], v[186:189], v[210:213], v[24:27]
	v_mfma_f32_16x16x32_bf16 v[16:19], v[178:181], v[218:221], v[16:19]
	v_mfma_f32_16x16x32_bf16 v[8:11], v[186:189], v[218:221], v[8:11]
	v_mfma_f32_16x16x32_bf16 v[4:7], v[178:181], v[226:229], v[4:7]
	v_mfma_f32_16x16x32_bf16 v[0:3], v[186:189], v[226:229], v[0:3]
	v_mfma_f32_16x16x32_bf16 v[48:51], v[182:185], v[202:205], v[48:51]
	v_mfma_f32_16x16x32_bf16 v[40:43], v[190:193], v[202:205], v[40:43]
	v_mfma_f32_16x16x32_bf16 v[32:35], v[182:185], v[214:217], v[32:35]
	v_mfma_f32_16x16x32_bf16 v[24:27], v[190:193], v[214:217], v[24:27]
	v_mfma_f32_16x16x32_bf16 v[16:19], v[182:185], v[222:225], v[16:19]
	v_mfma_f32_16x16x32_bf16 v[8:11], v[190:193], v[222:225], v[8:11]
	v_mfma_f32_16x16x32_bf16 v[4:7], v[182:185], v[230:233], v[4:7]
	v_mfma_f32_16x16x32_bf16 v[0:3], v[190:193], v[230:233], v[0:3]
	s_setprio 0
	s_barrier
	s_add_i32 s7, 0, 0x18000
	v_add_u32_e32 v138, s7, v169
	s_add_i32 s86, 0, 0x1c000
	ds_read_b128 v[148:151], v138
	ds_read_b128 v[152:155], v138 offset:1024
	ds_read_b128 v[156:159], v138 offset:2048
	ds_read_b128 v[160:163], v138 offset:3072
	v_add_u32_e32 v138, s86, v169
	ds_read_b128 v[178:181], v138
	ds_read_b128 v[182:185], v138 offset:1024
	ds_read_b128 v[186:189], v138 offset:2048
	ds_read_b128 v[190:193], v138 offset:3072
	v_lshl_add_u64 v[234:235], s[84:85], 0, v[130:131]
	s_mov_b32 m0, s65
	s_nop 0
	global_load_lds_dwordx4 v[234:235], off
	s_mov_b32 m0, s69
	s_nop 0
	global_load_lds_dwordx4 v[236:237], off
	s_add_u32 s24, s84, 0x40000
	s_addc_u32 s25, s85, 0
	s_mov_b32 m0, s87
	v_lshl_add_u64 v[238:239], s[24:25], 0, v[130:131]
	ds_read_b128 v[194:197], v174 offset:32768
	ds_read_b128 v[202:205], v174 offset:33792
	ds_read_b128 v[210:213], v174 offset:34816
	ds_read_b128 v[214:217], v174 offset:35840
	ds_read_b128 v[218:221], v174 offset:36864
	ds_read_b128 v[222:225], v174 offset:37888
	ds_read_b128 v[226:229], v174 offset:38912
	ds_read_b128 v[230:233], v174 offset:39936
	global_load_lds_dwordx4 v[238:239], off
	v_lshl_add_u64 v[238:239], s[24:25], 0, v[134:135]
	s_mov_b32 m0, s88
	s_nop 0
	global_load_lds_dwordx4 v[238:239], off
	s_waitcnt vmcnt(8) lgkmcnt(0)
	s_barrier
	s_setprio 1
	v_mfma_f32_16x16x32_bf16 v[124:127], v[148:151], v[194:197], v[124:127]
	v_mfma_f32_16x16x32_bf16 v[120:123], v[156:159], v[194:197], v[120:123]
	v_mfma_f32_16x16x32_bf16 v[112:115], v[148:151], v[210:213], v[112:115]
	v_mfma_f32_16x16x32_bf16 v[104:107], v[156:159], v[210:213], v[104:107]
	v_mfma_f32_16x16x32_bf16 v[100:103], v[148:151], v[218:221], v[100:103]
	v_mfma_f32_16x16x32_bf16 v[92:95], v[156:159], v[218:221], v[92:95]
	v_mfma_f32_16x16x32_bf16 v[84:87], v[148:151], v[226:229], v[84:87]
	v_mfma_f32_16x16x32_bf16 v[76:79], v[156:159], v[226:229], v[76:79]
	v_mfma_f32_16x16x32_bf16 v[124:127], v[152:155], v[202:205], v[124:127]
	v_mfma_f32_16x16x32_bf16 v[120:123], v[160:163], v[202:205], v[120:123]
	v_mfma_f32_16x16x32_bf16 v[112:115], v[152:155], v[214:217], v[112:115]
	v_mfma_f32_16x16x32_bf16 v[104:107], v[160:163], v[214:217], v[104:107]
	v_mfma_f32_16x16x32_bf16 v[100:103], v[152:155], v[222:225], v[100:103]
	v_mfma_f32_16x16x32_bf16 v[92:95], v[160:163], v[222:225], v[92:95]
	v_mfma_f32_16x16x32_bf16 v[84:87], v[152:155], v[230:233], v[84:87]
	v_mfma_f32_16x16x32_bf16 v[76:79], v[160:163], v[230:233], v[76:79]
	v_mfma_f32_16x16x32_bf16 v[116:119], v[178:181], v[194:197], v[116:119]
	v_mfma_f32_16x16x32_bf16 v[108:111], v[186:189], v[194:197], v[108:111]
	v_mfma_f32_16x16x32_bf16 v[96:99], v[178:181], v[210:213], v[96:99]
	v_mfma_f32_16x16x32_bf16 v[88:91], v[186:189], v[210:213], v[88:91]
	v_mfma_f32_16x16x32_bf16 v[80:83], v[178:181], v[218:221], v[80:83]
	v_mfma_f32_16x16x32_bf16 v[72:75], v[186:189], v[218:221], v[72:75]
	v_mfma_f32_16x16x32_bf16 v[68:71], v[178:181], v[226:229], v[68:71]
	v_mfma_f32_16x16x32_bf16 v[64:67], v[186:189], v[226:229], v[64:67]
	v_mfma_f32_16x16x32_bf16 v[116:119], v[182:185], v[202:205], v[116:119]
	v_mfma_f32_16x16x32_bf16 v[108:111], v[190:193], v[202:205], v[108:111]
	v_mfma_f32_16x16x32_bf16 v[96:99], v[182:185], v[214:217], v[96:99]
	v_mfma_f32_16x16x32_bf16 v[88:91], v[190:193], v[214:217], v[88:91]
	v_mfma_f32_16x16x32_bf16 v[80:83], v[182:185], v[222:225], v[80:83]
	v_mfma_f32_16x16x32_bf16 v[72:75], v[190:193], v[222:225], v[72:75]
	v_mfma_f32_16x16x32_bf16 v[68:71], v[182:185], v[230:233], v[68:71]
	v_mfma_f32_16x16x32_bf16 v[64:67], v[190:193], v[230:233], v[64:67]
	s_setprio 0
	s_barrier
	s_add_i32 s7, s7, s13
	v_lshl_add_u64 v[198:199], v[198:199], 0, s[66:67]
	s_mov_b32 m0, s7
	ds_read_b128 v[194:197], v174 offset:49152
	ds_read_b128 v[202:205], v174 offset:50176
	ds_read_b128 v[210:213], v174 offset:51200
	ds_read_b128 v[214:217], v174 offset:52224
	ds_read_b128 v[218:221], v174 offset:53248
	ds_read_b128 v[222:225], v174 offset:54272
	ds_read_b128 v[226:229], v174 offset:55296
	ds_read_b128 v[230:233], v174 offset:56320
	global_load_lds_dwordx4 v[198:199], off
	s_add_i32 m0, s7, 0x2000
	s_add_u32 s24, s82, 0x40080
	v_lshl_add_u64 v[198:199], v[206:207], 0, s[66:67]
	s_addc_u32 s25, s83, 0
	s_add_i32 s7, s86, s13
	global_load_lds_dwordx4 v[198:199], off
	v_lshl_add_u64 v[198:199], s[24:25], 0, v[132:133]
	s_mov_b32 m0, s7
	s_nop 0
	global_load_lds_dwordx4 v[198:199], off
	v_lshl_add_u64 v[198:199], s[24:25], 0, v[136:137]
	s_add_i32 m0, s7, 0x2000
	s_nop 0
	global_load_lds_dwordx4 v[198:199], off
	v_lshl_add_u64 v[198:199], v[234:235], 0, s[66:67]
	s_mov_b32 m0, s90
	s_nop 0
	global_load_lds_dwordx4 v[198:199], off
	v_lshl_add_u64 v[198:199], v[236:237], 0, s[66:67]
	s_mov_b32 m0, s91
	s_nop 0
	global_load_lds_dwordx4 v[198:199], off
	s_waitcnt vmcnt(6) lgkmcnt(0)
	s_barrier
	s_setprio 1
	v_mfma_f32_16x16x32_bf16 v[60:63], v[148:151], v[194:197], v[60:63]
	v_mfma_f32_16x16x32_bf16 v[56:59], v[156:159], v[194:197], v[56:59]
	v_mfma_f32_16x16x32_bf16 v[52:55], v[148:151], v[210:213], v[52:55]
	v_mfma_f32_16x16x32_bf16 v[44:47], v[156:159], v[210:213], v[44:47]
	v_mfma_f32_16x16x32_bf16 v[36:39], v[148:151], v[218:221], v[36:39]
	v_mfma_f32_16x16x32_bf16 v[28:31], v[156:159], v[218:221], v[28:31]
	v_mfma_f32_16x16x32_bf16 v[20:23], v[148:151], v[226:229], v[20:23]
	v_mfma_f32_16x16x32_bf16 v[12:15], v[156:159], v[226:229], v[12:15]
	v_mfma_f32_16x16x32_bf16 v[60:63], v[152:155], v[202:205], v[60:63]
	v_mfma_f32_16x16x32_bf16 v[56:59], v[160:163], v[202:205], v[56:59]
	v_mfma_f32_16x16x32_bf16 v[52:55], v[152:155], v[214:217], v[52:55]
	v_mfma_f32_16x16x32_bf16 v[44:47], v[160:163], v[214:217], v[44:47]
	v_mfma_f32_16x16x32_bf16 v[36:39], v[152:155], v[222:225], v[36:39]
	v_mfma_f32_16x16x32_bf16 v[28:31], v[160:163], v[222:225], v[28:31]
	v_mfma_f32_16x16x32_bf16 v[20:23], v[152:155], v[230:233], v[20:23]
	v_mfma_f32_16x16x32_bf16 v[12:15], v[160:163], v[230:233], v[12:15]
	v_mfma_f32_16x16x32_bf16 v[48:51], v[178:181], v[194:197], v[48:51]
	v_mfma_f32_16x16x32_bf16 v[40:43], v[186:189], v[194:197], v[40:43]
	v_mfma_f32_16x16x32_bf16 v[32:35], v[178:181], v[210:213], v[32:35]
	v_mfma_f32_16x16x32_bf16 v[24:27], v[186:189], v[210:213], v[24:27]
	v_mfma_f32_16x16x32_bf16 v[16:19], v[178:181], v[218:221], v[16:19]
	v_mfma_f32_16x16x32_bf16 v[8:11], v[186:189], v[218:221], v[8:11]
	v_mfma_f32_16x16x32_bf16 v[4:7], v[178:181], v[226:229], v[4:7]
	v_mfma_f32_16x16x32_bf16 v[0:3], v[186:189], v[226:229], v[0:3]
	v_mfma_f32_16x16x32_bf16 v[48:51], v[182:185], v[202:205], v[48:51]
	v_mfma_f32_16x16x32_bf16 v[40:43], v[190:193], v[202:205], v[40:43]
	v_mfma_f32_16x16x32_bf16 v[32:35], v[182:185], v[214:217], v[32:35]
	v_mfma_f32_16x16x32_bf16 v[24:27], v[190:193], v[214:217], v[24:27]
	v_mfma_f32_16x16x32_bf16 v[16:19], v[182:185], v[222:225], v[16:19]
	v_mfma_f32_16x16x32_bf16 v[8:11], v[190:193], v[222:225], v[8:11]
	v_mfma_f32_16x16x32_bf16 v[4:7], v[182:185], v[230:233], v[4:7]
	v_mfma_f32_16x16x32_bf16 v[0:3], v[190:193], v[230:233], v[0:3]
	s_setprio 0
	s_barrier
	s_add_i32 s6, s6, 2
	s_add_u32 s80, s80, 0x100
	s_addc_u32 s81, s81, 0
	s_add_u32 vcc_hi, vcc_hi, 0x100
	s_addc_u32 s33, s33, 0
	s_cmp_gt_u32 s6, 13
	s_cbranch_scc0 .LBB0_173
	s_and_b64 vcc, exec, s[70:71]
	s_cbranch_vccnz .LBB0_178
	v_lshl_add_u32 v148, s0, 8, v168
	s_cmp_gt_i32 s68, 3
	s_mov_b64 s[0:1], -1
	s_cbranch_scc1 .LBB0_179

.LBB0_241:
	ds_read_b128 v[154:157], v151
	ds_read_b128 v[158:161], v151 offset:1024
	ds_read_b128 v[168:171], v151 offset:2048
	ds_read_b128 v[172:175], v151 offset:3072
	ds_read_b128 v[178:181], v152
	ds_read_b128 v[182:185], v152 offset:1024
	ds_read_b128 v[186:189], v152 offset:2048
	ds_read_b128 v[190:193], v152 offset:3072
	s_add_u32 s24, s76, 0xfffc0080
	s_addc_u32 s25, s77, -1
	s_cmp_eq_u32 s86, 12
	s_cselect_b32 s81, s69, s25
	s_cselect_b32 s80, s75, s24
	s_cselect_b32 s79, s67, s33
	s_cselect_b32 s78, vcc_lo, vcc_hi
	v_lshl_add_u64 v[162:163], s[76:77], 0, v[140:141]
	s_add_i32 m0, s84, 0xc000
	ds_read_b128 v[194:197], v153
	ds_read_b128 v[202:205], v153 offset:1024
	ds_read_b128 v[210:213], v153 offset:2048
	ds_read_b128 v[214:217], v153 offset:3072
	ds_read_b128 v[218:221], v153 offset:4096
	ds_read_b128 v[222:225], v153 offset:5120
	ds_read_b128 v[226:229], v153 offset:6144
	ds_read_b128 v[230:233], v153 offset:7168
	global_load_lds_dwordx4 v[162:163], off
	v_lshl_add_u64 v[162:163], s[76:77], 0, v[142:143]
	s_add_i32 m0, s84, 0xe000
	s_nop 0
	global_load_lds_dwordx4 v[162:163], off
	s_waitcnt vmcnt(8) lgkmcnt(0)
	s_barrier
	s_setprio 1
	v_mfma_f32_16x16x32_bf16 v[124:127], v[154:157], v[194:197], v[124:127]
	v_mfma_f32_16x16x32_bf16 v[120:123], v[168:171], v[194:197], v[120:123]
	v_mfma_f32_16x16x32_bf16 v[112:115], v[154:157], v[210:213], v[112:115]
	v_mfma_f32_16x16x32_bf16 v[104:107], v[168:171], v[210:213], v[104:107]
	v_mfma_f32_16x16x32_bf16 v[100:103], v[154:157], v[218:221], v[100:103]
	v_mfma_f32_16x16x32_bf16 v[92:95], v[168:171], v[218:221], v[92:95]
	v_mfma_f32_16x16x32_bf16 v[84:87], v[154:157], v[226:229], v[84:87]
	v_mfma_f32_16x16x32_bf16 v[76:79], v[168:171], v[226:229], v[76:79]
	v_mfma_f32_16x16x32_bf16 v[124:127], v[158:161], v[202:205], v[124:127]
	v_mfma_f32_16x16x32_bf16 v[120:123], v[172:175], v[202:205], v[120:123]
	v_mfma_f32_16x16x32_bf16 v[112:115], v[158:161], v[214:217], v[112:115]
	v_mfma_f32_16x16x32_bf16 v[104:107], v[172:175], v[214:217], v[104:107]
	v_mfma_f32_16x16x32_bf16 v[100:103], v[158:161], v[222:225], v[100:103]
	v_mfma_f32_16x16x32_bf16 v[92:95], v[172:175], v[222:225], v[92:95]
	v_mfma_f32_16x16x32_bf16 v[84:87], v[158:161], v[230:233], v[84:87]
	v_mfma_f32_16x16x32_bf16 v[76:79], v[172:175], v[230:233], v[76:79]
	v_mfma_f32_16x16x32_bf16 v[116:119], v[178:181], v[194:197], v[116:119]
	v_mfma_f32_16x16x32_bf16 v[108:111], v[186:189], v[194:197], v[108:111]
	v_mfma_f32_16x16x32_bf16 v[96:99], v[178:181], v[210:213], v[96:99]
	v_mfma_f32_16x16x32_bf16 v[88:91], v[186:189], v[210:213], v[88:91]
	v_mfma_f32_16x16x32_bf16 v[80:83], v[178:181], v[218:221], v[80:83]
	v_mfma_f32_16x16x32_bf16 v[72:75], v[186:189], v[218:221], v[72:75]
	v_mfma_f32_16x16x32_bf16 v[68:71], v[178:181], v[226:229], v[68:71]
	v_mfma_f32_16x16x32_bf16 v[64:67], v[186:189], v[226:229], v[64:67]
	v_mfma_f32_16x16x32_bf16 v[116:119], v[182:185], v[202:205], v[116:119]
	v_mfma_f32_16x16x32_bf16 v[108:111], v[190:193], v[202:205], v[108:111]
	v_mfma_f32_16x16x32_bf16 v[96:99], v[182:185], v[214:217], v[96:99]
	v_mfma_f32_16x16x32_bf16 v[88:91], v[190:193], v[214:217], v[88:91]
	v_mfma_f32_16x16x32_bf16 v[80:83], v[182:185], v[222:225], v[80:83]
	v_mfma_f32_16x16x32_bf16 v[72:75], v[190:193], v[222:225], v[72:75]
	v_mfma_f32_16x16x32_bf16 v[68:71], v[182:185], v[230:233], v[68:71]
	v_mfma_f32_16x16x32_bf16 v[64:67], v[190:193], v[230:233], v[64:67]
	s_setprio 0
	s_barrier
	s_add_i32 s24, s94, s83
	v_lshl_add_u64 v[162:163], s[78:79], 0, v[132:133]
	s_mov_b32 m0, s24
	ds_read_b128 v[194:197], v153 offset:16384
	ds_read_b128 v[202:205], v153 offset:17408
	ds_read_b128 v[210:213], v153 offset:18432
	ds_read_b128 v[214:217], v153 offset:19456
	ds_read_b128 v[218:221], v153 offset:20480
	ds_read_b128 v[222:225], v153 offset:21504
	ds_read_b128 v[226:229], v153 offset:22528
	ds_read_b128 v[230:233], v153 offset:23552
	global_load_lds_dwordx4 v[162:163], off
	s_add_i32 m0, s24, 0x2000
	s_add_u32 s24, s78, 0x40000
	v_lshl_add_u64 v[198:199], s[78:79], 0, v[136:137]
	s_addc_u32 s25, s79, 0
	s_add_i32 s52, s95, s83
	global_load_lds_dwordx4 v[198:199], off
	v_lshl_add_u64 v[206:207], s[24:25], 0, v[132:133]
	s_mov_b32 m0, s52
	v_lshl_add_u64 v[234:235], s[80:81], 0, v[134:135]
	global_load_lds_dwordx4 v[206:207], off
	v_lshl_add_u64 v[206:207], s[24:25], 0, v[136:137]
	s_add_i32 m0, s52, 0x2000
	s_nop 0
	global_load_lds_dwordx4 v[206:207], off
	s_waitcnt vmcnt(6) lgkmcnt(0)
	s_barrier
	s_setprio 1
	v_mfma_f32_16x16x32_bf16 v[60:63], v[154:157], v[194:197], v[60:63]
	v_mfma_f32_16x16x32_bf16 v[56:59], v[168:171], v[194:197], v[56:59]
	v_mfma_f32_16x16x32_bf16 v[52:55], v[154:157], v[210:213], v[52:55]
	v_mfma_f32_16x16x32_bf16 v[44:47], v[168:171], v[210:213], v[44:47]
	v_mfma_f32_16x16x32_bf16 v[36:39], v[154:157], v[218:221], v[36:39]
	v_mfma_f32_16x16x32_bf16 v[28:31], v[168:171], v[218:221], v[28:31]
	v_mfma_f32_16x16x32_bf16 v[20:23], v[154:157], v[226:229], v[20:23]
	v_mfma_f32_16x16x32_bf16 v[12:15], v[168:171], v[226:229], v[12:15]
	v_mfma_f32_16x16x32_bf16 v[60:63], v[158:161], v[202:205], v[60:63]
	v_mfma_f32_16x16x32_bf16 v[56:59], v[172:175], v[202:205], v[56:59]
	v_mfma_f32_16x16x32_bf16 v[52:55], v[158:161], v[214:217], v[52:55]
	v_mfma_f32_16x16x32_bf16 v[44:47], v[172:175], v[214:217], v[44:47]
	v_mfma_f32_16x16x32_bf16 v[36:39], v[158:161], v[222:225], v[36:39]
	v_mfma_f32_16x16x32_bf16 v[28:31], v[172:175], v[222:225], v[28:31]
	v_mfma_f32_16x16x32_bf16 v[20:23], v[158:161], v[230:233], v[20:23]
	v_mfma_f32_16x16x32_bf16 v[12:15], v[172:175], v[230:233], v[12:15]
	v_mfma_f32_16x16x32_bf16 v[48:51], v[178:181], v[194:197], v[48:51]
	v_mfma_f32_16x16x32_bf16 v[40:43], v[186:189], v[194:197], v[40:43]
	v_mfma_f32_16x16x32_bf16 v[32:35], v[178:181], v[210:213], v[32:35]
	v_mfma_f32_16x16x32_bf16 v[24:27], v[186:189], v[210:213], v[24:27]
	v_mfma_f32_16x16x32_bf16 v[16:19], v[178:181], v[218:221], v[16:19]
	v_mfma_f32_16x16x32_bf16 v[8:11], v[186:189], v[218:221], v[8:11]
	v_mfma_f32_16x16x32_bf16 v[4:7], v[178:181], v[226:229], v[4:7]
	v_mfma_f32_16x16x32_bf16 v[0:3], v[186:189], v[226:229], v[0:3]
	v_mfma_f32_16x16x32_bf16 v[48:51], v[182:185], v[202:205], v[48:51]
	v_mfma_f32_16x16x32_bf16 v[40:43], v[190:193], v[202:205], v[40:43]
	v_mfma_f32_16x16x32_bf16 v[32:35], v[182:185], v[214:217], v[32:35]
	v_mfma_f32_16x16x32_bf16 v[24:27], v[190:193], v[214:217], v[24:27]
	v_mfma_f32_16x16x32_bf16 v[16:19], v[182:185], v[222:225], v[16:19]
	v_mfma_f32_16x16x32_bf16 v[8:11], v[190:193], v[222:225], v[8:11]
	v_mfma_f32_16x16x32_bf16 v[4:7], v[182:185], v[230:233], v[4:7]
	v_mfma_f32_16x16x32_bf16 v[0:3], v[190:193], v[230:233], v[0:3]
	s_setprio 0
	s_barrier
	s_add_i32 s52, 0, 0x18000
	v_add_u32_e32 v138, s52, v149
	s_add_i32 s53, 0, 0x1c000
	ds_read_b128 v[154:157], v138
	ds_read_b128 v[158:161], v138 offset:1024
	ds_read_b128 v[168:171], v138 offset:2048
	ds_read_b128 v[172:175], v138 offset:3072
	v_add_u32_e32 v138, s53, v149
	ds_read_b128 v[178:181], v138
	ds_read_b128 v[182:185], v138 offset:1024
	ds_read_b128 v[186:189], v138 offset:2048
	ds_read_b128 v[190:193], v138 offset:3072
	v_lshl_add_u64 v[206:207], s[80:81], 0, v[130:131]
	s_mov_b32 m0, s84
	s_nop 0
	global_load_lds_dwordx4 v[206:207], off
	s_mov_b32 m0, s85
	s_nop 0
	global_load_lds_dwordx4 v[234:235], off
	s_add_u32 s24, s80, 0x40000
	s_addc_u32 s25, s81, 0
	s_mov_b32 m0, s87
	v_lshl_add_u64 v[236:237], s[24:25], 0, v[130:131]
	ds_read_b128 v[194:197], v153 offset:32768
	ds_read_b128 v[202:205], v153 offset:33792
	ds_read_b128 v[210:213], v153 offset:34816
	ds_read_b128 v[214:217], v153 offset:35840
	ds_read_b128 v[218:221], v153 offset:36864
	ds_read_b128 v[222:225], v153 offset:37888
	ds_read_b128 v[226:229], v153 offset:38912
	ds_read_b128 v[230:233], v153 offset:39936
	global_load_lds_dwordx4 v[236:237], off
	v_lshl_add_u64 v[236:237], s[24:25], 0, v[134:135]
	s_mov_b32 m0, s88
	s_nop 0
	global_load_lds_dwordx4 v[236:237], off
	s_waitcnt vmcnt(8) lgkmcnt(0)
	s_barrier
	s_setprio 1
	v_mfma_f32_16x16x32_bf16 v[124:127], v[154:157], v[194:197], v[124:127]
	v_mfma_f32_16x16x32_bf16 v[120:123], v[168:171], v[194:197], v[120:123]
	v_mfma_f32_16x16x32_bf16 v[112:115], v[154:157], v[210:213], v[112:115]
	v_mfma_f32_16x16x32_bf16 v[104:107], v[168:171], v[210:213], v[104:107]
	v_mfma_f32_16x16x32_bf16 v[100:103], v[154:157], v[218:221], v[100:103]
	v_mfma_f32_16x16x32_bf16 v[92:95], v[168:171], v[218:221], v[92:95]
	v_mfma_f32_16x16x32_bf16 v[84:87], v[154:157], v[226:229], v[84:87]
	v_mfma_f32_16x16x32_bf16 v[76:79], v[168:171], v[226:229], v[76:79]
	v_mfma_f32_16x16x32_bf16 v[124:127], v[158:161], v[202:205], v[124:127]
	v_mfma_f32_16x16x32_bf16 v[120:123], v[172:175], v[202:205], v[120:123]
	v_mfma_f32_16x16x32_bf16 v[112:115], v[158:161], v[214:217], v[112:115]
	v_mfma_f32_16x16x32_bf16 v[104:107], v[172:175], v[214:217], v[104:107]
	v_mfma_f32_16x16x32_bf16 v[100:103], v[158:161], v[222:225], v[100:103]
	v_mfma_f32_16x16x32_bf16 v[92:95], v[172:175], v[222:225], v[92:95]
	v_mfma_f32_16x16x32_bf16 v[84:87], v[158:161], v[230:233], v[84:87]
	v_mfma_f32_16x16x32_bf16 v[76:79], v[172:175], v[230:233], v[76:79]
	v_mfma_f32_16x16x32_bf16 v[116:119], v[178:181], v[194:197], v[116:119]
	v_mfma_f32_16x16x32_bf16 v[108:111], v[186:189], v[194:197], v[108:111]
	v_mfma_f32_16x16x32_bf16 v[96:99], v[178:181], v[210:213], v[96:99]
	v_mfma_f32_16x16x32_bf16 v[88:91], v[186:189], v[210:213], v[88:91]
	v_mfma_f32_16x16x32_bf16 v[80:83], v[178:181], v[218:221], v[80:83]
	v_mfma_f32_16x16x32_bf16 v[72:75], v[186:189], v[218:221], v[72:75]
	v_mfma_f32_16x16x32_bf16 v[68:71], v[178:181], v[226:229], v[68:71]
	v_mfma_f32_16x16x32_bf16 v[64:67], v[186:189], v[226:229], v[64:67]
	v_mfma_f32_16x16x32_bf16 v[116:119], v[182:185], v[202:205], v[116:119]
	v_mfma_f32_16x16x32_bf16 v[108:111], v[190:193], v[202:205], v[108:111]
	v_mfma_f32_16x16x32_bf16 v[96:99], v[182:185], v[214:217], v[96:99]
	v_mfma_f32_16x16x32_bf16 v[88:91], v[190:193], v[214:217], v[88:91]
	v_mfma_f32_16x16x32_bf16 v[80:83], v[182:185], v[222:225], v[80:83]
	v_mfma_f32_16x16x32_bf16 v[72:75], v[190:193], v[222:225], v[72:75]
	v_mfma_f32_16x16x32_bf16 v[68:71], v[182:185], v[230:233], v[68:71]
	v_mfma_f32_16x16x32_bf16 v[64:67], v[190:193], v[230:233], v[64:67]
	s_setprio 0
	s_barrier
	s_add_i32 s24, s52, s83
	v_lshl_add_u64 v[162:163], v[162:163], 0, s[26:27]
	s_mov_b32 m0, s24
	ds_read_b128 v[194:197], v153 offset:49152
	ds_read_b128 v[202:205], v153 offset:50176
	ds_read_b128 v[210:213], v153 offset:51200
	ds_read_b128 v[214:217], v153 offset:52224
	ds_read_b128 v[218:221], v153 offset:53248
	ds_read_b128 v[222:225], v153 offset:54272
	ds_read_b128 v[226:229], v153 offset:55296
	ds_read_b128 v[230:233], v153 offset:56320
	global_load_lds_dwordx4 v[162:163], off
	s_add_i32 m0, s24, 0x2000
	s_add_u32 s24, s78, 0x40080
	v_lshl_add_u64 v[162:163], v[198:199], 0, s[26:27]
	s_addc_u32 s25, s79, 0
	s_add_i32 s52, s53, s83
	global_load_lds_dwordx4 v[162:163], off
	v_lshl_add_u64 v[162:163], s[24:25], 0, v[132:133]
	s_mov_b32 m0, s52
	s_nop 0
	global_load_lds_dwordx4 v[162:163], off
	v_lshl_add_u64 v[162:163], s[24:25], 0, v[136:137]
	s_add_i32 m0, s52, 0x2000
	s_nop 0
	global_load_lds_dwordx4 v[162:163], off
	v_lshl_add_u64 v[162:163], v[206:207], 0, s[26:27]
	s_mov_b32 m0, s90
	s_nop 0
	global_load_lds_dwordx4 v[162:163], off
	v_lshl_add_u64 v[162:163], v[234:235], 0, s[26:27]
	s_mov_b32 m0, s91
	s_nop 0
	global_load_lds_dwordx4 v[162:163], off
	s_waitcnt vmcnt(6) lgkmcnt(0)
	s_barrier
	s_setprio 1
	v_mfma_f32_16x16x32_bf16 v[60:63], v[154:157], v[194:197], v[60:63]
	v_mfma_f32_16x16x32_bf16 v[56:59], v[168:171], v[194:197], v[56:59]
	v_mfma_f32_16x16x32_bf16 v[52:55], v[154:157], v[210:213], v[52:55]
	v_mfma_f32_16x16x32_bf16 v[44:47], v[168:171], v[210:213], v[44:47]
	v_mfma_f32_16x16x32_bf16 v[36:39], v[154:157], v[218:221], v[36:39]
	v_mfma_f32_16x16x32_bf16 v[28:31], v[168:171], v[218:221], v[28:31]
	v_mfma_f32_16x16x32_bf16 v[20:23], v[154:157], v[226:229], v[20:23]
	v_mfma_f32_16x16x32_bf16 v[12:15], v[168:171], v[226:229], v[12:15]
	v_mfma_f32_16x16x32_bf16 v[60:63], v[158:161], v[202:205], v[60:63]
	v_mfma_f32_16x16x32_bf16 v[56:59], v[172:175], v[202:205], v[56:59]
	v_mfma_f32_16x16x32_bf16 v[52:55], v[158:161], v[214:217], v[52:55]
	v_mfma_f32_16x16x32_bf16 v[44:47], v[172:175], v[214:217], v[44:47]
	v_mfma_f32_16x16x32_bf16 v[36:39], v[158:161], v[222:225], v[36:39]
	v_mfma_f32_16x16x32_bf16 v[28:31], v[172:175], v[222:225], v[28:31]
	v_mfma_f32_16x16x32_bf16 v[20:23], v[158:161], v[230:233], v[20:23]
	v_mfma_f32_16x16x32_bf16 v[12:15], v[172:175], v[230:233], v[12:15]
	v_mfma_f32_16x16x32_bf16 v[48:51], v[178:181], v[194:197], v[48:51]
	v_mfma_f32_16x16x32_bf16 v[40:43], v[186:189], v[194:197], v[40:43]
	v_mfma_f32_16x16x32_bf16 v[32:35], v[178:181], v[210:213], v[32:35]
	v_mfma_f32_16x16x32_bf16 v[24:27], v[186:189], v[210:213], v[24:27]
	v_mfma_f32_16x16x32_bf16 v[16:19], v[178:181], v[218:221], v[16:19]
	v_mfma_f32_16x16x32_bf16 v[8:11], v[186:189], v[218:221], v[8:11]
	v_mfma_f32_16x16x32_bf16 v[4:7], v[178:181], v[226:229], v[4:7]
	v_mfma_f32_16x16x32_bf16 v[0:3], v[186:189], v[226:229], v[0:3]
	v_mfma_f32_16x16x32_bf16 v[48:51], v[182:185], v[202:205], v[48:51]
	v_mfma_f32_16x16x32_bf16 v[40:43], v[190:193], v[202:205], v[40:43]
	v_mfma_f32_16x16x32_bf16 v[32:35], v[182:185], v[214:217], v[32:35]
	v_mfma_f32_16x16x32_bf16 v[24:27], v[190:193], v[214:217], v[24:27]
	v_mfma_f32_16x16x32_bf16 v[16:19], v[182:185], v[222:225], v[16:19]
	v_mfma_f32_16x16x32_bf16 v[8:11], v[190:193], v[222:225], v[8:11]
	v_mfma_f32_16x16x32_bf16 v[4:7], v[182:185], v[230:233], v[4:7]
	v_mfma_f32_16x16x32_bf16 v[0:3], v[190:193], v[230:233], v[0:3]
	s_setprio 0
	s_barrier
	s_add_i32 s86, s86, 2
	s_add_u32 s76, s76, 0x100
	s_addc_u32 s77, s77, 0
	s_add_u32 vcc_hi, vcc_hi, 0x100
	s_addc_u32 s33, s33, 0
	s_cmp_gt_u32 s86, 13
	s_cbranch_scc0 .LBB0_241
	s_and_b64 vcc, exec, s[34:35]
	s_cbranch_vccz .LBB0_244
	s_barrier

.LBB0_462:
	v_add_u32_e32 v156, s83, v161
	v_add_u32_e32 v176, s84, v161
	ds_read_b128 v[144:147], v156
	ds_read_b128 v[148:151], v156 offset:1024
	ds_read_b128 v[152:155], v156 offset:2048
	ds_read_b128 v[156:159], v156 offset:3072
	ds_read_b128 v[164:167], v176
	ds_read_b128 v[168:171], v176 offset:1024
	ds_read_b128 v[172:175], v176 offset:2048
	ds_read_b128 v[176:179], v176 offset:3072
	s_add_u32 s58, s70, 0xfffe0080
	s_addc_u32 s59, s71, -1
	s_cmp_eq_u32 s95, 4
	s_cselect_b32 s75, s57, s59
	s_cselect_b32 s74, s91, s58
	s_cselect_b32 s73, s55, s94
	s_cselect_b32 s72, s92, s93
	v_lshl_add_u64 v[216:217], s[70:71], 0, v[136:137]
	s_add_i32 m0, s77, 0xc000
	ds_read_b128 v[180:183], v163
	ds_read_b128 v[184:187], v163 offset:1024
	ds_read_b128 v[188:191], v163 offset:2048
	ds_read_b128 v[192:195], v163 offset:3072
	ds_read_b128 v[196:199], v163 offset:4096
	ds_read_b128 v[200:203], v163 offset:5120
	ds_read_b128 v[204:207], v163 offset:6144
	ds_read_b128 v[212:215], v163 offset:7168
	global_load_lds_dwordx4 v[216:217], off
	v_lshl_add_u64 v[216:217], s[70:71], 0, v[138:139]
	s_add_i32 m0, s77, 0xe000
	s_nop 0
	global_load_lds_dwordx4 v[216:217], off
	s_waitcnt vmcnt(8) lgkmcnt(0)
	s_barrier
	s_setprio 1
	v_mfma_f32_16x16x32_bf16 v[124:127], v[144:147], v[180:183], v[124:127]
	v_mfma_f32_16x16x32_bf16 v[120:123], v[152:155], v[180:183], v[120:123]
	v_mfma_f32_16x16x32_bf16 v[116:119], v[144:147], v[188:191], v[116:119]
	v_mfma_f32_16x16x32_bf16 v[112:115], v[152:155], v[188:191], v[112:115]
	v_mfma_f32_16x16x32_bf16 v[108:111], v[144:147], v[196:199], v[108:111]
	v_mfma_f32_16x16x32_bf16 v[104:107], v[152:155], v[196:199], v[104:107]
	v_mfma_f32_16x16x32_bf16 v[100:103], v[144:147], v[204:207], v[100:103]
	v_mfma_f32_16x16x32_bf16 v[96:99], v[152:155], v[204:207], v[96:99]
	v_mfma_f32_16x16x32_bf16 v[124:127], v[148:151], v[184:187], v[124:127]
	v_mfma_f32_16x16x32_bf16 v[120:123], v[156:159], v[184:187], v[120:123]
	v_mfma_f32_16x16x32_bf16 v[116:119], v[148:151], v[192:195], v[116:119]
	v_mfma_f32_16x16x32_bf16 v[112:115], v[156:159], v[192:195], v[112:115]
	v_mfma_f32_16x16x32_bf16 v[108:111], v[148:151], v[200:203], v[108:111]
	v_mfma_f32_16x16x32_bf16 v[104:107], v[156:159], v[200:203], v[104:107]
	v_mfma_f32_16x16x32_bf16 v[100:103], v[148:151], v[212:215], v[100:103]
	v_mfma_f32_16x16x32_bf16 v[96:99], v[156:159], v[212:215], v[96:99]
	v_mfma_f32_16x16x32_bf16 v[92:95], v[164:167], v[180:183], v[92:95]
	v_mfma_f32_16x16x32_bf16 v[88:91], v[172:175], v[180:183], v[88:91]
	v_mfma_f32_16x16x32_bf16 v[84:87], v[164:167], v[188:191], v[84:87]
	v_mfma_f32_16x16x32_bf16 v[80:83], v[172:175], v[188:191], v[80:83]
	v_mfma_f32_16x16x32_bf16 v[76:79], v[164:167], v[196:199], v[76:79]
	v_mfma_f32_16x16x32_bf16 v[72:75], v[172:175], v[196:199], v[72:75]
	v_mfma_f32_16x16x32_bf16 v[68:71], v[164:167], v[204:207], v[68:71]
	v_mfma_f32_16x16x32_bf16 v[64:67], v[172:175], v[204:207], v[64:67]
	v_mfma_f32_16x16x32_bf16 v[92:95], v[168:171], v[184:187], v[92:95]
	v_mfma_f32_16x16x32_bf16 v[88:91], v[176:179], v[184:187], v[88:91]
	v_mfma_f32_16x16x32_bf16 v[84:87], v[168:171], v[192:195], v[84:87]
	v_mfma_f32_16x16x32_bf16 v[80:83], v[176:179], v[192:195], v[80:83]
	v_mfma_f32_16x16x32_bf16 v[76:79], v[168:171], v[200:203], v[76:79]
	v_mfma_f32_16x16x32_bf16 v[72:75], v[176:179], v[200:203], v[72:75]
	v_mfma_f32_16x16x32_bf16 v[68:71], v[168:171], v[212:215], v[68:71]
	v_mfma_f32_16x16x32_bf16 v[64:67], v[176:179], v[212:215], v[64:67]
	s_setprio 0
	s_barrier
	s_add_i32 s58, s83, s76
	v_lshl_add_u64 v[216:217], s[72:73], 0, v[130:131]
	s_mov_b32 m0, s58
	ds_read_b128 v[180:183], v163 offset:16384
	ds_read_b128 v[184:187], v163 offset:17408
	ds_read_b128 v[188:191], v163 offset:18432
	ds_read_b128 v[192:195], v163 offset:19456
	ds_read_b128 v[196:199], v163 offset:20480
	ds_read_b128 v[200:203], v163 offset:21504
	ds_read_b128 v[204:207], v163 offset:22528
	ds_read_b128 v[212:215], v163 offset:23552
	global_load_lds_dwordx4 v[216:217], off
	s_add_i32 m0, s58, 0x2000
	s_add_u32 s96, s72, 0x20000
	v_lshl_add_u64 v[218:219], s[72:73], 0, v[134:135]
	s_addc_u32 s97, s73, 0
	s_add_i32 s58, s84, s76
	global_load_lds_dwordx4 v[218:219], off
	v_lshl_add_u64 v[220:221], s[96:97], 0, v[130:131]
	s_mov_b32 m0, s58
	v_lshl_add_u64 v[222:223], s[74:75], 0, v[132:133]
	global_load_lds_dwordx4 v[220:221], off
	v_lshl_add_u64 v[220:221], s[96:97], 0, v[134:135]
	s_add_i32 m0, s58, 0x2000
	s_nop 0
	global_load_lds_dwordx4 v[220:221], off
	s_waitcnt vmcnt(6) lgkmcnt(0)
	s_barrier
	s_setprio 1
	v_mfma_f32_16x16x32_bf16 v[60:63], v[144:147], v[180:183], v[60:63]
	v_mfma_f32_16x16x32_bf16 v[56:59], v[152:155], v[180:183], v[56:59]
	v_mfma_f32_16x16x32_bf16 v[52:55], v[144:147], v[188:191], v[52:55]
	v_mfma_f32_16x16x32_bf16 v[48:51], v[152:155], v[188:191], v[48:51]
	v_mfma_f32_16x16x32_bf16 v[44:47], v[144:147], v[196:199], v[44:47]
	v_mfma_f32_16x16x32_bf16 v[40:43], v[152:155], v[196:199], v[40:43]
	v_mfma_f32_16x16x32_bf16 v[36:39], v[144:147], v[204:207], v[36:39]
	v_mfma_f32_16x16x32_bf16 v[32:35], v[152:155], v[204:207], v[32:35]
	v_mfma_f32_16x16x32_bf16 v[60:63], v[148:151], v[184:187], v[60:63]
	v_mfma_f32_16x16x32_bf16 v[56:59], v[156:159], v[184:187], v[56:59]
	v_mfma_f32_16x16x32_bf16 v[52:55], v[148:151], v[192:195], v[52:55]
	v_mfma_f32_16x16x32_bf16 v[48:51], v[156:159], v[192:195], v[48:51]
	v_mfma_f32_16x16x32_bf16 v[44:47], v[148:151], v[200:203], v[44:47]
	v_mfma_f32_16x16x32_bf16 v[40:43], v[156:159], v[200:203], v[40:43]
	v_mfma_f32_16x16x32_bf16 v[36:39], v[148:151], v[212:215], v[36:39]
	v_mfma_f32_16x16x32_bf16 v[32:35], v[156:159], v[212:215], v[32:35]
	v_mfma_f32_16x16x32_bf16 v[28:31], v[164:167], v[180:183], v[28:31]
	v_mfma_f32_16x16x32_bf16 v[24:27], v[172:175], v[180:183], v[24:27]
	v_mfma_f32_16x16x32_bf16 v[20:23], v[164:167], v[188:191], v[20:23]
	v_mfma_f32_16x16x32_bf16 v[16:19], v[172:175], v[188:191], v[16:19]
	v_mfma_f32_16x16x32_bf16 v[12:15], v[164:167], v[196:199], v[12:15]
	v_mfma_f32_16x16x32_bf16 v[8:11], v[172:175], v[196:199], v[8:11]
	v_mfma_f32_16x16x32_bf16 v[4:7], v[164:167], v[204:207], v[4:7]
	v_mfma_f32_16x16x32_bf16 v[0:3], v[172:175], v[204:207], v[0:3]
	v_mfma_f32_16x16x32_bf16 v[28:31], v[168:171], v[184:187], v[28:31]
	v_mfma_f32_16x16x32_bf16 v[24:27], v[176:179], v[184:187], v[24:27]
	v_mfma_f32_16x16x32_bf16 v[20:23], v[168:171], v[192:195], v[20:23]
	v_mfma_f32_16x16x32_bf16 v[16:19], v[176:179], v[192:195], v[16:19]
	v_mfma_f32_16x16x32_bf16 v[12:15], v[168:171], v[200:203], v[12:15]
	v_mfma_f32_16x16x32_bf16 v[8:11], v[176:179], v[200:203], v[8:11]
	v_mfma_f32_16x16x32_bf16 v[4:7], v[168:171], v[212:215], v[4:7]
	v_mfma_f32_16x16x32_bf16 v[0:3], v[176:179], v[212:215], v[0:3]
	s_setprio 0
	s_barrier
	s_add_i32 s58, 0, 0x18000
	s_add_i32 s59, 0, 0x1c000
	v_add_u32_e32 v156, s58, v161
	v_add_u32_e32 v176, s59, v161
	ds_read_b128 v[144:147], v156
	ds_read_b128 v[148:151], v156 offset:1024
	ds_read_b128 v[152:155], v156 offset:2048
	ds_read_b128 v[156:159], v156 offset:3072
	ds_read_b128 v[164:167], v176
	ds_read_b128 v[168:171], v176 offset:1024
	ds_read_b128 v[172:175], v176 offset:2048
	ds_read_b128 v[176:179], v176 offset:3072
	v_lshl_add_u64 v[220:221], s[74:75], 0, v[128:129]
	s_mov_b32 m0, s77
	s_nop 0
	global_load_lds_dwordx4 v[220:221], off
	s_mov_b32 m0, s78
	s_nop 0
	global_load_lds_dwordx4 v[222:223], off
	s_add_u32 s74, s74, 0x20000
	s_addc_u32 s75, s75, 0
	s_mov_b32 m0, s79
	v_lshl_add_u64 v[224:225], s[74:75], 0, v[128:129]
	ds_read_b128 v[180:183], v163 offset:32768
	ds_read_b128 v[184:187], v163 offset:33792
	ds_read_b128 v[188:191], v163 offset:34816
	ds_read_b128 v[192:195], v163 offset:35840
	ds_read_b128 v[196:199], v163 offset:36864
	ds_read_b128 v[200:203], v163 offset:37888
	ds_read_b128 v[204:207], v163 offset:38912
	ds_read_b128 v[212:215], v163 offset:39936
	global_load_lds_dwordx4 v[224:225], off
	v_lshl_add_u64 v[224:225], s[74:75], 0, v[132:133]
	s_mov_b32 m0, s80
	s_nop 0
	global_load_lds_dwordx4 v[224:225], off
	s_waitcnt vmcnt(8) lgkmcnt(0)
	s_barrier
	s_setprio 1
	v_mfma_f32_16x16x32_bf16 v[124:127], v[144:147], v[180:183], v[124:127]
	v_mfma_f32_16x16x32_bf16 v[120:123], v[152:155], v[180:183], v[120:123]
	v_mfma_f32_16x16x32_bf16 v[116:119], v[144:147], v[188:191], v[116:119]
	v_mfma_f32_16x16x32_bf16 v[112:115], v[152:155], v[188:191], v[112:115]
	v_mfma_f32_16x16x32_bf16 v[108:111], v[144:147], v[196:199], v[108:111]
	v_mfma_f32_16x16x32_bf16 v[104:107], v[152:155], v[196:199], v[104:107]
	v_mfma_f32_16x16x32_bf16 v[100:103], v[144:147], v[204:207], v[100:103]
	v_mfma_f32_16x16x32_bf16 v[96:99], v[152:155], v[204:207], v[96:99]
	v_mfma_f32_16x16x32_bf16 v[124:127], v[148:151], v[184:187], v[124:127]
	v_mfma_f32_16x16x32_bf16 v[120:123], v[156:159], v[184:187], v[120:123]
	v_mfma_f32_16x16x32_bf16 v[116:119], v[148:151], v[192:195], v[116:119]
	v_mfma_f32_16x16x32_bf16 v[112:115], v[156:159], v[192:195], v[112:115]
	v_mfma_f32_16x16x32_bf16 v[108:111], v[148:151], v[200:203], v[108:111]
	v_mfma_f32_16x16x32_bf16 v[104:107], v[156:159], v[200:203], v[104:107]
	v_mfma_f32_16x16x32_bf16 v[100:103], v[148:151], v[212:215], v[100:103]
	v_mfma_f32_16x16x32_bf16 v[96:99], v[156:159], v[212:215], v[96:99]
	v_mfma_f32_16x16x32_bf16 v[92:95], v[164:167], v[180:183], v[92:95]
	v_mfma_f32_16x16x32_bf16 v[88:91], v[172:175], v[180:183], v[88:91]
	v_mfma_f32_16x16x32_bf16 v[84:87], v[164:167], v[188:191], v[84:87]
	v_mfma_f32_16x16x32_bf16 v[80:83], v[172:175], v[188:191], v[80:83]
	v_mfma_f32_16x16x32_bf16 v[76:79], v[164:167], v[196:199], v[76:79]
	v_mfma_f32_16x16x32_bf16 v[72:75], v[172:175], v[196:199], v[72:75]
	v_mfma_f32_16x16x32_bf16 v[68:71], v[164:167], v[204:207], v[68:71]
	v_mfma_f32_16x16x32_bf16 v[64:67], v[172:175], v[204:207], v[64:67]
	v_mfma_f32_16x16x32_bf16 v[92:95], v[168:171], v[184:187], v[92:95]
	v_mfma_f32_16x16x32_bf16 v[88:91], v[176:179], v[184:187], v[88:91]
	v_mfma_f32_16x16x32_bf16 v[84:87], v[168:171], v[192:195], v[84:87]
	v_mfma_f32_16x16x32_bf16 v[80:83], v[176:179], v[192:195], v[80:83]
	v_mfma_f32_16x16x32_bf16 v[76:79], v[168:171], v[200:203], v[76:79]
	v_mfma_f32_16x16x32_bf16 v[72:75], v[176:179], v[200:203], v[72:75]
	v_mfma_f32_16x16x32_bf16 v[68:71], v[168:171], v[212:215], v[68:71]
	v_mfma_f32_16x16x32_bf16 v[64:67], v[176:179], v[212:215], v[64:67]
	s_setprio 0
	s_barrier
	s_add_i32 s58, s58, s76
	v_lshl_add_u64 v[216:217], v[216:217], 0, s[38:39]
	s_mov_b32 m0, s58
	ds_read_b128 v[180:183], v163 offset:49152
	ds_read_b128 v[184:187], v163 offset:50176
	ds_read_b128 v[188:191], v163 offset:51200
	ds_read_b128 v[192:195], v163 offset:52224
	ds_read_b128 v[196:199], v163 offset:53248
	ds_read_b128 v[200:203], v163 offset:54272
	ds_read_b128 v[204:207], v163 offset:55296
	ds_read_b128 v[212:215], v163 offset:56320
	global_load_lds_dwordx4 v[216:217], off
	s_add_i32 m0, s58, 0x2000
	s_add_u32 s72, s72, 0x20080
	v_lshl_add_u64 v[216:217], v[218:219], 0, s[38:39]
	s_addc_u32 s73, s73, 0
	s_add_i32 s58, s59, s76
	global_load_lds_dwordx4 v[216:217], off
	v_lshl_add_u64 v[216:217], s[72:73], 0, v[130:131]
	s_mov_b32 m0, s58
	s_nop 0
	global_load_lds_dwordx4 v[216:217], off
	v_lshl_add_u64 v[216:217], s[72:73], 0, v[134:135]
	s_add_i32 m0, s58, 0x2000
	s_nop 0
	global_load_lds_dwordx4 v[216:217], off
	v_lshl_add_u64 v[216:217], v[220:221], 0, s[38:39]
	s_mov_b32 m0, s81
	s_nop 0
	global_load_lds_dwordx4 v[216:217], off
	v_lshl_add_u64 v[216:217], v[222:223], 0, s[38:39]
	s_mov_b32 m0, s82
	s_nop 0
	global_load_lds_dwordx4 v[216:217], off
	s_waitcnt vmcnt(6) lgkmcnt(0)
	s_barrier
	s_setprio 1
	v_mfma_f32_16x16x32_bf16 v[60:63], v[144:147], v[180:183], v[60:63]
	v_mfma_f32_16x16x32_bf16 v[56:59], v[152:155], v[180:183], v[56:59]
	v_mfma_f32_16x16x32_bf16 v[52:55], v[144:147], v[188:191], v[52:55]
	v_mfma_f32_16x16x32_bf16 v[48:51], v[152:155], v[188:191], v[48:51]
	v_mfma_f32_16x16x32_bf16 v[44:47], v[144:147], v[196:199], v[44:47]
	v_mfma_f32_16x16x32_bf16 v[40:43], v[152:155], v[196:199], v[40:43]
	v_mfma_f32_16x16x32_bf16 v[36:39], v[144:147], v[204:207], v[36:39]
	v_mfma_f32_16x16x32_bf16 v[32:35], v[152:155], v[204:207], v[32:35]
	v_mfma_f32_16x16x32_bf16 v[60:63], v[148:151], v[184:187], v[60:63]
	v_mfma_f32_16x16x32_bf16 v[56:59], v[156:159], v[184:187], v[56:59]
	v_mfma_f32_16x16x32_bf16 v[52:55], v[148:151], v[192:195], v[52:55]
	v_mfma_f32_16x16x32_bf16 v[48:51], v[156:159], v[192:195], v[48:51]
	v_mfma_f32_16x16x32_bf16 v[44:47], v[148:151], v[200:203], v[44:47]
	v_mfma_f32_16x16x32_bf16 v[40:43], v[156:159], v[200:203], v[40:43]
	v_mfma_f32_16x16x32_bf16 v[36:39], v[148:151], v[212:215], v[36:39]
	v_mfma_f32_16x16x32_bf16 v[32:35], v[156:159], v[212:215], v[32:35]
	v_mfma_f32_16x16x32_bf16 v[28:31], v[164:167], v[180:183], v[28:31]
	v_mfma_f32_16x16x32_bf16 v[24:27], v[172:175], v[180:183], v[24:27]
	v_mfma_f32_16x16x32_bf16 v[20:23], v[164:167], v[188:191], v[20:23]
	v_mfma_f32_16x16x32_bf16 v[16:19], v[172:175], v[188:191], v[16:19]
	v_mfma_f32_16x16x32_bf16 v[12:15], v[164:167], v[196:199], v[12:15]
	v_mfma_f32_16x16x32_bf16 v[8:11], v[172:175], v[196:199], v[8:11]
	v_mfma_f32_16x16x32_bf16 v[4:7], v[164:167], v[204:207], v[4:7]
	v_mfma_f32_16x16x32_bf16 v[0:3], v[172:175], v[204:207], v[0:3]
	v_mfma_f32_16x16x32_bf16 v[28:31], v[168:171], v[184:187], v[28:31]
	v_mfma_f32_16x16x32_bf16 v[24:27], v[176:179], v[184:187], v[24:27]
	v_mfma_f32_16x16x32_bf16 v[20:23], v[168:171], v[192:195], v[20:23]
	v_mfma_f32_16x16x32_bf16 v[16:19], v[176:179], v[192:195], v[16:19]
	v_mfma_f32_16x16x32_bf16 v[12:15], v[168:171], v[200:203], v[12:15]
	v_mfma_f32_16x16x32_bf16 v[8:11], v[176:179], v[200:203], v[8:11]
	v_mfma_f32_16x16x32_bf16 v[4:7], v[168:171], v[212:215], v[4:7]
	v_mfma_f32_16x16x32_bf16 v[0:3], v[176:179], v[212:215], v[0:3]
	s_setprio 0
	s_barrier
	s_add_i32 s95, s95, 2
	s_add_u32 s70, s70, 0x100
	s_addc_u32 s71, s71, 0
	s_add_u32 s93, s93, 0x100
	s_addc_u32 s94, s94, 0
	s_cmp_gt_u32 s95, 5
	s_cbranch_scc0 .LBB0_462
	s_and_b64 vcc, exec, s[40:41]
	s_cbranch_vccz .LBB0_465
	s_barrier

.LBB0_544:
	ds_read_b128 v[100:103], v199
	ds_read_b128 v[108:111], v199 offset:1024
	ds_read_b128 v[112:115], v199 offset:2048
	ds_read_b128 v[116:119], v199 offset:3072
	ds_read_b128 v[156:159], v200
	ds_read_b128 v[160:163], v200 offset:1024
	ds_read_b128 v[164:167], v200 offset:2048
	ds_read_b128 v[168:171], v200 offset:3072
	s_add_u32 s56, s54, 0xfffc0080
	s_addc_u32 s57, s55, -1
	s_cmp_eq_u32 s88, 12
	s_cselect_b32 s65, s43, s57
	s_cselect_b32 s64, s49, s56
	s_cselect_b32 s57, s41, s33
	s_cselect_b32 s56, s53, s87
	v_lshl_add_u64 v[216:217], s[54:55], 0, v[148:149]
	s_add_i32 m0, s67, 0xc000
	ds_read_b128 v[172:175], v201
	ds_read_b128 v[176:179], v201 offset:1024
	ds_read_b128 v[180:183], v201 offset:2048
	ds_read_b128 v[184:187], v201 offset:3072
	ds_read_b128 v[188:191], v201 offset:4096
	ds_read_b128 v[192:195], v201 offset:5120
	ds_read_b128 v[204:207], v201 offset:6144
	ds_read_b128 v[212:215], v201 offset:7168
	global_load_lds_dwordx4 v[216:217], off
	v_lshl_add_u64 v[216:217], s[54:55], 0, v[150:151]
	s_add_i32 m0, s67, 0xe000
	s_nop 0
	global_load_lds_dwordx4 v[216:217], off
	s_waitcnt vmcnt(8) lgkmcnt(0)
	s_barrier
	s_setprio 1
	v_mfma_f32_16x16x32_bf16 v[140:143], v[100:103], v[172:175], v[140:143]
	v_mfma_f32_16x16x32_bf16 v[136:139], v[112:115], v[172:175], v[136:139]
	v_mfma_f32_16x16x32_bf16 v[124:127], v[100:103], v[180:183], v[124:127]
	v_mfma_f32_16x16x32_bf16 v[120:123], v[112:115], v[180:183], v[120:123]
	v_mfma_f32_16x16x32_bf16 v[92:95], v[100:103], v[188:191], v[92:95]
	v_mfma_f32_16x16x32_bf16 v[88:91], v[112:115], v[188:191], v[88:91]
	v_mfma_f32_16x16x32_bf16 v[76:79], v[100:103], v[204:207], v[76:79]
	v_mfma_f32_16x16x32_bf16 v[72:75], v[112:115], v[204:207], v[72:75]
	v_mfma_f32_16x16x32_bf16 v[140:143], v[108:111], v[176:179], v[140:143]
	v_mfma_f32_16x16x32_bf16 v[136:139], v[116:119], v[176:179], v[136:139]
	v_mfma_f32_16x16x32_bf16 v[124:127], v[108:111], v[184:187], v[124:127]
	v_mfma_f32_16x16x32_bf16 v[120:123], v[116:119], v[184:187], v[120:123]
	v_mfma_f32_16x16x32_bf16 v[92:95], v[108:111], v[192:195], v[92:95]
	v_mfma_f32_16x16x32_bf16 v[88:91], v[116:119], v[192:195], v[88:91]
	v_mfma_f32_16x16x32_bf16 v[76:79], v[108:111], v[212:215], v[76:79]
	v_mfma_f32_16x16x32_bf16 v[72:75], v[116:119], v[212:215], v[72:75]
	v_mfma_f32_16x16x32_bf16 v[132:135], v[156:159], v[172:175], v[132:135]
	v_mfma_f32_16x16x32_bf16 v[128:131], v[164:167], v[172:175], v[128:131]
	v_mfma_f32_16x16x32_bf16 v[104:107], v[156:159], v[180:183], v[104:107]
	v_mfma_f32_16x16x32_bf16 v[96:99], v[164:167], v[180:183], v[96:99]
	v_mfma_f32_16x16x32_bf16 v[84:87], v[156:159], v[188:191], v[84:87]
	v_mfma_f32_16x16x32_bf16 v[80:83], v[164:167], v[188:191], v[80:83]
	v_mfma_f32_16x16x32_bf16 v[68:71], v[156:159], v[204:207], v[68:71]
	v_mfma_f32_16x16x32_bf16 v[64:67], v[164:167], v[204:207], v[64:67]
	v_mfma_f32_16x16x32_bf16 v[132:135], v[160:163], v[176:179], v[132:135]
	v_mfma_f32_16x16x32_bf16 v[128:131], v[168:171], v[176:179], v[128:131]
	v_mfma_f32_16x16x32_bf16 v[104:107], v[160:163], v[184:187], v[104:107]
	v_mfma_f32_16x16x32_bf16 v[96:99], v[168:171], v[184:187], v[96:99]
	v_mfma_f32_16x16x32_bf16 v[84:87], v[160:163], v[192:195], v[84:87]
	v_mfma_f32_16x16x32_bf16 v[80:83], v[168:171], v[192:195], v[80:83]
	v_mfma_f32_16x16x32_bf16 v[68:71], v[160:163], v[212:215], v[68:71]
	v_mfma_f32_16x16x32_bf16 v[64:67], v[168:171], v[212:215], v[64:67]
	s_setprio 0
	s_barrier
	s_add_i32 s58, s85, s66
	v_lshl_add_u64 v[216:217], s[56:57], 0, v[144:145]
	s_mov_b32 m0, s58
	ds_read_b128 v[172:175], v201 offset:16384
	ds_read_b128 v[176:179], v201 offset:17408
	ds_read_b128 v[180:183], v201 offset:18432
	ds_read_b128 v[184:187], v201 offset:19456
	ds_read_b128 v[188:191], v201 offset:20480
	ds_read_b128 v[192:195], v201 offset:21504
	ds_read_b128 v[204:207], v201 offset:22528
	ds_read_b128 v[212:215], v201 offset:23552
	global_load_lds_dwordx4 v[216:217], off
	s_add_i32 m0, s58, 0x2000
	s_add_u32 s90, s56, 0x40000
	v_lshl_add_u64 v[218:219], s[56:57], 0, v[146:147]
	s_addc_u32 s91, s57, 0
	s_add_i32 s58, s86, s66
	global_load_lds_dwordx4 v[218:219], off
	v_lshl_add_u64 v[220:221], s[90:91], 0, v[144:145]
	s_mov_b32 m0, s58
	v_lshl_add_u64 v[222:223], s[64:65], 0, v[146:147]
	global_load_lds_dwordx4 v[220:221], off
	v_lshl_add_u64 v[220:221], s[90:91], 0, v[146:147]
	s_add_i32 m0, s58, 0x2000
	s_nop 0
	global_load_lds_dwordx4 v[220:221], off
	s_waitcnt vmcnt(6) lgkmcnt(0)
	s_barrier
	s_setprio 1
	v_mfma_f32_16x16x32_bf16 v[60:63], v[100:103], v[172:175], v[60:63]
	v_mfma_f32_16x16x32_bf16 v[56:59], v[112:115], v[172:175], v[56:59]
	v_mfma_f32_16x16x32_bf16 v[44:47], v[100:103], v[180:183], v[44:47]
	v_mfma_f32_16x16x32_bf16 v[40:43], v[112:115], v[180:183], v[40:43]
	v_mfma_f32_16x16x32_bf16 v[28:31], v[100:103], v[188:191], v[28:31]
	v_mfma_f32_16x16x32_bf16 v[24:27], v[112:115], v[188:191], v[24:27]
	v_mfma_f32_16x16x32_bf16 v[12:15], v[100:103], v[204:207], v[12:15]
	v_mfma_f32_16x16x32_bf16 v[8:11], v[112:115], v[204:207], v[8:11]
	v_mfma_f32_16x16x32_bf16 v[60:63], v[108:111], v[176:179], v[60:63]
	v_mfma_f32_16x16x32_bf16 v[56:59], v[116:119], v[176:179], v[56:59]
	v_mfma_f32_16x16x32_bf16 v[44:47], v[108:111], v[184:187], v[44:47]
	v_mfma_f32_16x16x32_bf16 v[40:43], v[116:119], v[184:187], v[40:43]
	v_mfma_f32_16x16x32_bf16 v[28:31], v[108:111], v[192:195], v[28:31]
	v_mfma_f32_16x16x32_bf16 v[24:27], v[116:119], v[192:195], v[24:27]
	v_mfma_f32_16x16x32_bf16 v[12:15], v[108:111], v[212:215], v[12:15]
	v_mfma_f32_16x16x32_bf16 v[8:11], v[116:119], v[212:215], v[8:11]
	v_mfma_f32_16x16x32_bf16 v[52:55], v[156:159], v[172:175], v[52:55]
	v_mfma_f32_16x16x32_bf16 v[48:51], v[164:167], v[172:175], v[48:51]
	v_mfma_f32_16x16x32_bf16 v[36:39], v[156:159], v[180:183], v[36:39]
	v_mfma_f32_16x16x32_bf16 v[32:35], v[164:167], v[180:183], v[32:35]
	v_mfma_f32_16x16x32_bf16 v[20:23], v[156:159], v[188:191], v[20:23]
	v_mfma_f32_16x16x32_bf16 v[16:19], v[164:167], v[188:191], v[16:19]
	v_mfma_f32_16x16x32_bf16 v[4:7], v[156:159], v[204:207], v[4:7]
	v_mfma_f32_16x16x32_bf16 v[0:3], v[164:167], v[204:207], v[0:3]
	v_mfma_f32_16x16x32_bf16 v[52:55], v[160:163], v[176:179], v[52:55]
	v_mfma_f32_16x16x32_bf16 v[48:51], v[168:171], v[176:179], v[48:51]
	v_mfma_f32_16x16x32_bf16 v[36:39], v[160:163], v[184:187], v[36:39]
	v_mfma_f32_16x16x32_bf16 v[32:35], v[168:171], v[184:187], v[32:35]
	v_mfma_f32_16x16x32_bf16 v[20:23], v[160:163], v[192:195], v[20:23]
	v_mfma_f32_16x16x32_bf16 v[16:19], v[168:171], v[192:195], v[16:19]
	v_mfma_f32_16x16x32_bf16 v[4:7], v[160:163], v[212:215], v[4:7]
	v_mfma_f32_16x16x32_bf16 v[0:3], v[168:171], v[212:215], v[0:3]
	s_setprio 0
	s_barrier
	s_add_i32 s58, 0, 0x18000
	s_add_i32 s59, 0, 0x1c000
	v_add_u32_e32 v116, s58, v197
	v_add_u32_e32 v168, s59, v197
	ds_read_b128 v[100:103], v116
	ds_read_b128 v[108:111], v116 offset:1024
	ds_read_b128 v[112:115], v116 offset:2048
	ds_read_b128 v[116:119], v116 offset:3072
	ds_read_b128 v[156:159], v168
	ds_read_b128 v[160:163], v168 offset:1024
	ds_read_b128 v[164:167], v168 offset:2048
	ds_read_b128 v[168:171], v168 offset:3072
	v_lshl_add_u64 v[220:221], s[64:65], 0, v[144:145]
	s_mov_b32 m0, s67
	s_nop 0
	global_load_lds_dwordx4 v[220:221], off
	s_mov_b32 m0, s68
	s_nop 0
	global_load_lds_dwordx4 v[222:223], off
	s_add_u32 s64, s64, 0x40000
	s_addc_u32 s65, s65, 0
	s_mov_b32 m0, s69
	v_lshl_add_u64 v[224:225], s[64:65], 0, v[144:145]
	ds_read_b128 v[172:175], v201 offset:32768
	ds_read_b128 v[176:179], v201 offset:33792
	ds_read_b128 v[180:183], v201 offset:34816
	ds_read_b128 v[184:187], v201 offset:35840
	ds_read_b128 v[188:191], v201 offset:36864
	ds_read_b128 v[192:195], v201 offset:37888
	ds_read_b128 v[204:207], v201 offset:38912
	ds_read_b128 v[212:215], v201 offset:39936
	global_load_lds_dwordx4 v[224:225], off
	v_lshl_add_u64 v[224:225], s[64:65], 0, v[146:147]
	s_mov_b32 m0, s70
	s_nop 0
	global_load_lds_dwordx4 v[224:225], off
	s_waitcnt vmcnt(8) lgkmcnt(0)
	s_barrier
	s_setprio 1
	v_mfma_f32_16x16x32_bf16 v[140:143], v[100:103], v[172:175], v[140:143]
	v_mfma_f32_16x16x32_bf16 v[136:139], v[112:115], v[172:175], v[136:139]
	v_mfma_f32_16x16x32_bf16 v[124:127], v[100:103], v[180:183], v[124:127]
	v_mfma_f32_16x16x32_bf16 v[120:123], v[112:115], v[180:183], v[120:123]
	v_mfma_f32_16x16x32_bf16 v[92:95], v[100:103], v[188:191], v[92:95]
	v_mfma_f32_16x16x32_bf16 v[88:91], v[112:115], v[188:191], v[88:91]
	v_mfma_f32_16x16x32_bf16 v[76:79], v[100:103], v[204:207], v[76:79]
	v_mfma_f32_16x16x32_bf16 v[72:75], v[112:115], v[204:207], v[72:75]
	v_mfma_f32_16x16x32_bf16 v[140:143], v[108:111], v[176:179], v[140:143]
	v_mfma_f32_16x16x32_bf16 v[136:139], v[116:119], v[176:179], v[136:139]
	v_mfma_f32_16x16x32_bf16 v[124:127], v[108:111], v[184:187], v[124:127]
	v_mfma_f32_16x16x32_bf16 v[120:123], v[116:119], v[184:187], v[120:123]
	v_mfma_f32_16x16x32_bf16 v[92:95], v[108:111], v[192:195], v[92:95]
	v_mfma_f32_16x16x32_bf16 v[88:91], v[116:119], v[192:195], v[88:91]
	v_mfma_f32_16x16x32_bf16 v[76:79], v[108:111], v[212:215], v[76:79]
	v_mfma_f32_16x16x32_bf16 v[72:75], v[116:119], v[212:215], v[72:75]
	v_mfma_f32_16x16x32_bf16 v[132:135], v[156:159], v[172:175], v[132:135]
	v_mfma_f32_16x16x32_bf16 v[128:131], v[164:167], v[172:175], v[128:131]
	v_mfma_f32_16x16x32_bf16 v[104:107], v[156:159], v[180:183], v[104:107]
	v_mfma_f32_16x16x32_bf16 v[96:99], v[164:167], v[180:183], v[96:99]
	v_mfma_f32_16x16x32_bf16 v[84:87], v[156:159], v[188:191], v[84:87]
	v_mfma_f32_16x16x32_bf16 v[80:83], v[164:167], v[188:191], v[80:83]
	v_mfma_f32_16x16x32_bf16 v[68:71], v[156:159], v[204:207], v[68:71]
	v_mfma_f32_16x16x32_bf16 v[64:67], v[164:167], v[204:207], v[64:67]
	v_mfma_f32_16x16x32_bf16 v[132:135], v[160:163], v[176:179], v[132:135]
	v_mfma_f32_16x16x32_bf16 v[128:131], v[168:171], v[176:179], v[128:131]
	v_mfma_f32_16x16x32_bf16 v[104:107], v[160:163], v[184:187], v[104:107]
	v_mfma_f32_16x16x32_bf16 v[96:99], v[168:171], v[184:187], v[96:99]
	v_mfma_f32_16x16x32_bf16 v[84:87], v[160:163], v[192:195], v[84:87]
	v_mfma_f32_16x16x32_bf16 v[80:83], v[168:171], v[192:195], v[80:83]
	v_mfma_f32_16x16x32_bf16 v[68:71], v[160:163], v[212:215], v[68:71]
	v_mfma_f32_16x16x32_bf16 v[64:67], v[168:171], v[212:215], v[64:67]
	s_setprio 0
	s_barrier
	s_add_i32 s58, s58, s66
	v_lshl_add_u64 v[216:217], v[216:217], 0, s[36:37]
	s_mov_b32 m0, s58
	ds_read_b128 v[172:175], v201 offset:49152
	ds_read_b128 v[176:179], v201 offset:50176
	ds_read_b128 v[180:183], v201 offset:51200
	ds_read_b128 v[184:187], v201 offset:52224
	ds_read_b128 v[188:191], v201 offset:53248
	ds_read_b128 v[192:195], v201 offset:54272
	ds_read_b128 v[204:207], v201 offset:55296
	ds_read_b128 v[212:215], v201 offset:56320
	global_load_lds_dwordx4 v[216:217], off
	s_add_i32 m0, s58, 0x2000
	s_add_u32 s56, s56, 0x40080
	v_lshl_add_u64 v[216:217], v[218:219], 0, s[36:37]
	s_addc_u32 s57, s57, 0
	s_add_i32 s58, s59, s66
	global_load_lds_dwordx4 v[216:217], off
	v_lshl_add_u64 v[216:217], s[56:57], 0, v[144:145]
	s_mov_b32 m0, s58
	s_nop 0
	global_load_lds_dwordx4 v[216:217], off
	v_lshl_add_u64 v[216:217], s[56:57], 0, v[146:147]
	s_add_i32 m0, s58, 0x2000
	s_nop 0
	global_load_lds_dwordx4 v[216:217], off
	v_lshl_add_u64 v[216:217], v[220:221], 0, s[36:37]
	s_mov_b32 m0, s80
	s_nop 0
	global_load_lds_dwordx4 v[216:217], off
	v_lshl_add_u64 v[216:217], v[222:223], 0, s[36:37]
	s_mov_b32 m0, s81
	s_nop 0
	global_load_lds_dwordx4 v[216:217], off
	s_waitcnt vmcnt(6) lgkmcnt(0)
	s_barrier
	s_setprio 1
	v_mfma_f32_16x16x32_bf16 v[60:63], v[100:103], v[172:175], v[60:63]
	v_mfma_f32_16x16x32_bf16 v[56:59], v[112:115], v[172:175], v[56:59]
	v_mfma_f32_16x16x32_bf16 v[44:47], v[100:103], v[180:183], v[44:47]
	v_mfma_f32_16x16x32_bf16 v[40:43], v[112:115], v[180:183], v[40:43]
	v_mfma_f32_16x16x32_bf16 v[28:31], v[100:103], v[188:191], v[28:31]
	v_mfma_f32_16x16x32_bf16 v[24:27], v[112:115], v[188:191], v[24:27]
	v_mfma_f32_16x16x32_bf16 v[12:15], v[100:103], v[204:207], v[12:15]
	v_mfma_f32_16x16x32_bf16 v[8:11], v[112:115], v[204:207], v[8:11]
	v_mfma_f32_16x16x32_bf16 v[60:63], v[108:111], v[176:179], v[60:63]
	v_mfma_f32_16x16x32_bf16 v[56:59], v[116:119], v[176:179], v[56:59]
	v_mfma_f32_16x16x32_bf16 v[44:47], v[108:111], v[184:187], v[44:47]
	v_mfma_f32_16x16x32_bf16 v[40:43], v[116:119], v[184:187], v[40:43]
	v_mfma_f32_16x16x32_bf16 v[28:31], v[108:111], v[192:195], v[28:31]
	v_mfma_f32_16x16x32_bf16 v[24:27], v[116:119], v[192:195], v[24:27]
	v_mfma_f32_16x16x32_bf16 v[12:15], v[108:111], v[212:215], v[12:15]
	v_mfma_f32_16x16x32_bf16 v[8:11], v[116:119], v[212:215], v[8:11]
	v_mfma_f32_16x16x32_bf16 v[52:55], v[156:159], v[172:175], v[52:55]
	v_mfma_f32_16x16x32_bf16 v[48:51], v[164:167], v[172:175], v[48:51]
	v_mfma_f32_16x16x32_bf16 v[36:39], v[156:159], v[180:183], v[36:39]
	v_mfma_f32_16x16x32_bf16 v[32:35], v[164:167], v[180:183], v[32:35]
	v_mfma_f32_16x16x32_bf16 v[20:23], v[156:159], v[188:191], v[20:23]
	v_mfma_f32_16x16x32_bf16 v[16:19], v[164:167], v[188:191], v[16:19]
	v_mfma_f32_16x16x32_bf16 v[4:7], v[156:159], v[204:207], v[4:7]
	v_mfma_f32_16x16x32_bf16 v[0:3], v[164:167], v[204:207], v[0:3]
	v_mfma_f32_16x16x32_bf16 v[52:55], v[160:163], v[176:179], v[52:55]
	v_mfma_f32_16x16x32_bf16 v[48:51], v[168:171], v[176:179], v[48:51]
	v_mfma_f32_16x16x32_bf16 v[36:39], v[160:163], v[184:187], v[36:39]
	v_mfma_f32_16x16x32_bf16 v[32:35], v[168:171], v[184:187], v[32:35]
	v_mfma_f32_16x16x32_bf16 v[20:23], v[160:163], v[192:195], v[20:23]
	v_mfma_f32_16x16x32_bf16 v[16:19], v[168:171], v[192:195], v[16:19]
	v_mfma_f32_16x16x32_bf16 v[4:7], v[160:163], v[212:215], v[4:7]
	v_mfma_f32_16x16x32_bf16 v[0:3], v[168:171], v[212:215], v[0:3]
	s_setprio 0
	s_barrier
	s_add_i32 s88, s88, 2
	s_add_u32 s54, s54, 0x100
	s_addc_u32 s55, s55, 0
	s_add_u32 s87, s87, 0x100
	s_addc_u32 s33, s33, 0
	s_cmp_gt_u32 s88, 13
	s_cbranch_scc0 .LBB0_544
	s_and_b64 vcc, exec, s[38:39]
	s_cbranch_vccz .LBB0_547
	s_barrier

.LBB0_639:
	ds_read_b128 v[144:147], v151
	ds_read_b128 v[154:157], v151 offset:1024
	ds_read_b128 v[158:161], v151 offset:2048
	ds_read_b128 v[162:165], v151 offset:3072
	ds_read_b128 v[166:169], v152
	ds_read_b128 v[170:173], v152 offset:1024
	ds_read_b128 v[174:177], v152 offset:2048
	ds_read_b128 v[178:181], v152 offset:3072
	s_add_u32 s40, s38, 0xfffc0080
	s_addc_u32 s41, s39, -1
	s_cmp_eq_u32 s68, 12
	s_cselect_b32 s43, s21, s41
	s_cselect_b32 s42, s65, s40
	s_cselect_b32 s41, s17, s33
	s_cselect_b32 s40, s66, s67
	v_lshl_add_u64 v[206:207], s[38:39], 0, v[136:137]
	s_add_i32 m0, s37, 0xc000
	ds_read_b128 v[182:185], v153
	ds_read_b128 v[186:189], v153 offset:1024
	ds_read_b128 v[190:193], v153 offset:2048
	ds_read_b128 v[194:197], v153 offset:3072
	ds_read_b128 v[198:201], v153 offset:4096
	ds_read_b128 v[202:205], v153 offset:5120
	ds_read_b128 v[212:215], v153 offset:6144
	ds_read_b128 v[216:219], v153 offset:7168
	global_load_lds_dwordx4 v[206:207], off
	v_lshl_add_u64 v[206:207], s[38:39], 0, v[138:139]
	s_add_i32 m0, s37, 0xe000
	s_nop 0
	global_load_lds_dwordx4 v[206:207], off
	s_waitcnt vmcnt(8) lgkmcnt(0)
	s_barrier
	s_setprio 1
	v_mfma_f32_16x16x32_bf16 v[124:127], v[144:147], v[182:185], v[124:127]
	v_mfma_f32_16x16x32_bf16 v[116:119], v[158:161], v[182:185], v[116:119]
	v_mfma_f32_16x16x32_bf16 v[108:111], v[144:147], v[190:193], v[108:111]
	v_mfma_f32_16x16x32_bf16 v[100:103], v[158:161], v[190:193], v[100:103]
	v_mfma_f32_16x16x32_bf16 v[92:95], v[144:147], v[198:201], v[92:95]
	v_mfma_f32_16x16x32_bf16 v[84:87], v[158:161], v[198:201], v[84:87]
	v_mfma_f32_16x16x32_bf16 v[76:79], v[144:147], v[212:215], v[76:79]
	v_mfma_f32_16x16x32_bf16 v[68:71], v[158:161], v[212:215], v[68:71]
	v_mfma_f32_16x16x32_bf16 v[124:127], v[154:157], v[186:189], v[124:127]
	v_mfma_f32_16x16x32_bf16 v[116:119], v[162:165], v[186:189], v[116:119]
	v_mfma_f32_16x16x32_bf16 v[108:111], v[154:157], v[194:197], v[108:111]
	v_mfma_f32_16x16x32_bf16 v[100:103], v[162:165], v[194:197], v[100:103]
	v_mfma_f32_16x16x32_bf16 v[92:95], v[154:157], v[202:205], v[92:95]
	v_mfma_f32_16x16x32_bf16 v[84:87], v[162:165], v[202:205], v[84:87]
	v_mfma_f32_16x16x32_bf16 v[76:79], v[154:157], v[216:219], v[76:79]
	v_mfma_f32_16x16x32_bf16 v[68:71], v[162:165], v[216:219], v[68:71]
	v_mfma_f32_16x16x32_bf16 v[120:123], v[166:169], v[182:185], v[120:123]
	v_mfma_f32_16x16x32_bf16 v[112:115], v[174:177], v[182:185], v[112:115]
	v_mfma_f32_16x16x32_bf16 v[104:107], v[166:169], v[190:193], v[104:107]
	v_mfma_f32_16x16x32_bf16 v[96:99], v[174:177], v[190:193], v[96:99]
	v_mfma_f32_16x16x32_bf16 v[88:91], v[166:169], v[198:201], v[88:91]
	v_mfma_f32_16x16x32_bf16 v[80:83], v[174:177], v[198:201], v[80:83]
	v_mfma_f32_16x16x32_bf16 v[72:75], v[166:169], v[212:215], v[72:75]
	v_mfma_f32_16x16x32_bf16 v[64:67], v[174:177], v[212:215], v[64:67]
	v_mfma_f32_16x16x32_bf16 v[120:123], v[170:173], v[186:189], v[120:123]
	v_mfma_f32_16x16x32_bf16 v[112:115], v[178:181], v[186:189], v[112:115]
	v_mfma_f32_16x16x32_bf16 v[104:107], v[170:173], v[194:197], v[104:107]
	v_mfma_f32_16x16x32_bf16 v[96:99], v[178:181], v[194:197], v[96:99]
	v_mfma_f32_16x16x32_bf16 v[88:91], v[170:173], v[202:205], v[88:91]
	v_mfma_f32_16x16x32_bf16 v[80:83], v[178:181], v[202:205], v[80:83]
	v_mfma_f32_16x16x32_bf16 v[72:75], v[170:173], v[216:219], v[72:75]
	v_mfma_f32_16x16x32_bf16 v[64:67], v[178:181], v[216:219], v[64:67]
	s_setprio 0
	s_barrier
	s_add_i32 s58, s55, s44
	v_lshl_add_u64 v[206:207], s[40:41], 0, v[132:133]
	s_mov_b32 m0, s58
	ds_read_b128 v[182:185], v153 offset:16384
	ds_read_b128 v[186:189], v153 offset:17408
	ds_read_b128 v[190:193], v153 offset:18432
	ds_read_b128 v[194:197], v153 offset:19456
	ds_read_b128 v[198:201], v153 offset:20480
	ds_read_b128 v[202:205], v153 offset:21504
	ds_read_b128 v[212:215], v153 offset:22528
	ds_read_b128 v[216:219], v153 offset:23552
	global_load_lds_dwordx4 v[206:207], off
	s_add_i32 m0, s58, 0x2000
	s_add_u32 s70, s40, 0x40000
	v_lshl_add_u64 v[220:221], s[40:41], 0, v[128:129]
	s_addc_u32 s71, s41, 0
	s_add_i32 s58, s56, s44
	global_load_lds_dwordx4 v[220:221], off
	v_lshl_add_u64 v[222:223], s[70:71], 0, v[132:133]
	s_mov_b32 m0, s58
	v_lshl_add_u64 v[224:225], s[42:43], 0, v[130:131]
	global_load_lds_dwordx4 v[222:223], off
	v_lshl_add_u64 v[222:223], s[70:71], 0, v[128:129]
	s_add_i32 m0, s58, 0x2000
	s_nop 0
	global_load_lds_dwordx4 v[222:223], off
	s_waitcnt vmcnt(6) lgkmcnt(0)
	s_barrier
	s_setprio 1
	v_mfma_f32_16x16x32_bf16 v[60:63], v[144:147], v[182:185], v[60:63]
	v_mfma_f32_16x16x32_bf16 v[52:55], v[158:161], v[182:185], v[52:55]
	v_mfma_f32_16x16x32_bf16 v[44:47], v[144:147], v[190:193], v[44:47]
	v_mfma_f32_16x16x32_bf16 v[36:39], v[158:161], v[190:193], v[36:39]
	v_mfma_f32_16x16x32_bf16 v[28:31], v[144:147], v[198:201], v[28:31]
	v_mfma_f32_16x16x32_bf16 v[20:23], v[158:161], v[198:201], v[20:23]
	v_mfma_f32_16x16x32_bf16 v[12:15], v[144:147], v[212:215], v[12:15]
	v_mfma_f32_16x16x32_bf16 v[4:7], v[158:161], v[212:215], v[4:7]
	v_mfma_f32_16x16x32_bf16 v[60:63], v[154:157], v[186:189], v[60:63]
	v_mfma_f32_16x16x32_bf16 v[52:55], v[162:165], v[186:189], v[52:55]
	v_mfma_f32_16x16x32_bf16 v[44:47], v[154:157], v[194:197], v[44:47]
	v_mfma_f32_16x16x32_bf16 v[36:39], v[162:165], v[194:197], v[36:39]
	v_mfma_f32_16x16x32_bf16 v[28:31], v[154:157], v[202:205], v[28:31]
	v_mfma_f32_16x16x32_bf16 v[20:23], v[162:165], v[202:205], v[20:23]
	v_mfma_f32_16x16x32_bf16 v[12:15], v[154:157], v[216:219], v[12:15]
	v_mfma_f32_16x16x32_bf16 v[4:7], v[162:165], v[216:219], v[4:7]
	v_mfma_f32_16x16x32_bf16 v[56:59], v[166:169], v[182:185], v[56:59]
	v_mfma_f32_16x16x32_bf16 v[48:51], v[174:177], v[182:185], v[48:51]
	v_mfma_f32_16x16x32_bf16 v[40:43], v[166:169], v[190:193], v[40:43]
	v_mfma_f32_16x16x32_bf16 v[32:35], v[174:177], v[190:193], v[32:35]
	v_mfma_f32_16x16x32_bf16 v[24:27], v[166:169], v[198:201], v[24:27]
	v_mfma_f32_16x16x32_bf16 v[16:19], v[174:177], v[198:201], v[16:19]
	v_mfma_f32_16x16x32_bf16 v[8:11], v[166:169], v[212:215], v[8:11]
	v_mfma_f32_16x16x32_bf16 v[0:3], v[174:177], v[212:215], v[0:3]
	v_mfma_f32_16x16x32_bf16 v[56:59], v[170:173], v[186:189], v[56:59]
	v_mfma_f32_16x16x32_bf16 v[48:51], v[178:181], v[186:189], v[48:51]
	v_mfma_f32_16x16x32_bf16 v[40:43], v[170:173], v[194:197], v[40:43]
	v_mfma_f32_16x16x32_bf16 v[32:35], v[178:181], v[194:197], v[32:35]
	v_mfma_f32_16x16x32_bf16 v[24:27], v[170:173], v[202:205], v[24:27]
	v_mfma_f32_16x16x32_bf16 v[16:19], v[178:181], v[202:205], v[16:19]
	v_mfma_f32_16x16x32_bf16 v[8:11], v[170:173], v[216:219], v[8:11]
	v_mfma_f32_16x16x32_bf16 v[0:3], v[178:181], v[216:219], v[0:3]
	s_setprio 0
	s_barrier
	s_add_i32 s58, 0, 0x18000
	s_add_i32 s59, 0, 0x1c000
	v_add_u32_e32 v162, s58, v149
	v_add_u32_e32 v178, s59, v149
	ds_read_b128 v[144:147], v162
	ds_read_b128 v[154:157], v162 offset:1024
	ds_read_b128 v[158:161], v162 offset:2048
	ds_read_b128 v[162:165], v162 offset:3072
	ds_read_b128 v[166:169], v178
	ds_read_b128 v[170:173], v178 offset:1024
	ds_read_b128 v[174:177], v178 offset:2048
	ds_read_b128 v[178:181], v178 offset:3072
	v_lshl_add_u64 v[222:223], s[42:43], 0, v[134:135]
	s_mov_b32 m0, s37
	s_nop 0
	global_load_lds_dwordx4 v[222:223], off
	s_mov_b32 m0, s47
	s_nop 0
	global_load_lds_dwordx4 v[224:225], off
	s_add_u32 s42, s42, 0x40000
	s_addc_u32 s43, s43, 0
	s_mov_b32 m0, s48
	v_lshl_add_u64 v[226:227], s[42:43], 0, v[134:135]
	ds_read_b128 v[182:185], v153 offset:32768
	ds_read_b128 v[186:189], v153 offset:33792
	ds_read_b128 v[190:193], v153 offset:34816
	ds_read_b128 v[194:197], v153 offset:35840
	ds_read_b128 v[198:201], v153 offset:36864
	ds_read_b128 v[202:205], v153 offset:37888
	ds_read_b128 v[212:215], v153 offset:38912
	ds_read_b128 v[216:219], v153 offset:39936
	global_load_lds_dwordx4 v[226:227], off
	v_lshl_add_u64 v[226:227], s[42:43], 0, v[130:131]
	s_mov_b32 m0, s49
	s_nop 0
	global_load_lds_dwordx4 v[226:227], off
	s_waitcnt vmcnt(8) lgkmcnt(0)
	s_barrier
	s_setprio 1
	v_mfma_f32_16x16x32_bf16 v[124:127], v[144:147], v[182:185], v[124:127]
	v_mfma_f32_16x16x32_bf16 v[116:119], v[158:161], v[182:185], v[116:119]
	v_mfma_f32_16x16x32_bf16 v[108:111], v[144:147], v[190:193], v[108:111]
	v_mfma_f32_16x16x32_bf16 v[100:103], v[158:161], v[190:193], v[100:103]
	v_mfma_f32_16x16x32_bf16 v[92:95], v[144:147], v[198:201], v[92:95]
	v_mfma_f32_16x16x32_bf16 v[84:87], v[158:161], v[198:201], v[84:87]
	v_mfma_f32_16x16x32_bf16 v[76:79], v[144:147], v[212:215], v[76:79]
	v_mfma_f32_16x16x32_bf16 v[68:71], v[158:161], v[212:215], v[68:71]
	v_mfma_f32_16x16x32_bf16 v[124:127], v[154:157], v[186:189], v[124:127]
	v_mfma_f32_16x16x32_bf16 v[116:119], v[162:165], v[186:189], v[116:119]
	v_mfma_f32_16x16x32_bf16 v[108:111], v[154:157], v[194:197], v[108:111]
	v_mfma_f32_16x16x32_bf16 v[100:103], v[162:165], v[194:197], v[100:103]
	v_mfma_f32_16x16x32_bf16 v[92:95], v[154:157], v[202:205], v[92:95]
	v_mfma_f32_16x16x32_bf16 v[84:87], v[162:165], v[202:205], v[84:87]
	v_mfma_f32_16x16x32_bf16 v[76:79], v[154:157], v[216:219], v[76:79]
	v_mfma_f32_16x16x32_bf16 v[68:71], v[162:165], v[216:219], v[68:71]
	v_mfma_f32_16x16x32_bf16 v[120:123], v[166:169], v[182:185], v[120:123]
	v_mfma_f32_16x16x32_bf16 v[112:115], v[174:177], v[182:185], v[112:115]
	v_mfma_f32_16x16x32_bf16 v[104:107], v[166:169], v[190:193], v[104:107]
	v_mfma_f32_16x16x32_bf16 v[96:99], v[174:177], v[190:193], v[96:99]
	v_mfma_f32_16x16x32_bf16 v[88:91], v[166:169], v[198:201], v[88:91]
	v_mfma_f32_16x16x32_bf16 v[80:83], v[174:177], v[198:201], v[80:83]
	v_mfma_f32_16x16x32_bf16 v[72:75], v[166:169], v[212:215], v[72:75]
	v_mfma_f32_16x16x32_bf16 v[64:67], v[174:177], v[212:215], v[64:67]
	v_mfma_f32_16x16x32_bf16 v[120:123], v[170:173], v[186:189], v[120:123]
	v_mfma_f32_16x16x32_bf16 v[112:115], v[178:181], v[186:189], v[112:115]
	v_mfma_f32_16x16x32_bf16 v[104:107], v[170:173], v[194:197], v[104:107]
	v_mfma_f32_16x16x32_bf16 v[96:99], v[178:181], v[194:197], v[96:99]
	v_mfma_f32_16x16x32_bf16 v[88:91], v[170:173], v[202:205], v[88:91]
	v_mfma_f32_16x16x32_bf16 v[80:83], v[178:181], v[202:205], v[80:83]
	v_mfma_f32_16x16x32_bf16 v[72:75], v[170:173], v[216:219], v[72:75]
	v_mfma_f32_16x16x32_bf16 v[64:67], v[178:181], v[216:219], v[64:67]
	s_setprio 0
	s_barrier
	s_add_i32 s42, s58, s44
	v_lshl_add_u64 v[206:207], v[206:207], 0, s[6:7]
	s_mov_b32 m0, s42
	ds_read_b128 v[182:185], v153 offset:49152
	ds_read_b128 v[186:189], v153 offset:50176
	ds_read_b128 v[190:193], v153 offset:51200
	ds_read_b128 v[194:197], v153 offset:52224
	ds_read_b128 v[198:201], v153 offset:53248
	ds_read_b128 v[202:205], v153 offset:54272
	ds_read_b128 v[212:215], v153 offset:55296
	ds_read_b128 v[216:219], v153 offset:56320
	global_load_lds_dwordx4 v[206:207], off
	s_add_i32 m0, s42, 0x2000
	s_add_u32 s40, s40, 0x40080
	v_lshl_add_u64 v[206:207], v[220:221], 0, s[6:7]
	s_addc_u32 s41, s41, 0
	s_add_i32 s42, s59, s44
	global_load_lds_dwordx4 v[206:207], off
	v_lshl_add_u64 v[206:207], s[40:41], 0, v[132:133]
	s_mov_b32 m0, s42
	s_nop 0
	global_load_lds_dwordx4 v[206:207], off
	v_lshl_add_u64 v[206:207], s[40:41], 0, v[128:129]
	s_add_i32 m0, s42, 0x2000
	s_nop 0
	global_load_lds_dwordx4 v[206:207], off
	v_lshl_add_u64 v[206:207], v[222:223], 0, s[6:7]
	s_mov_b32 m0, s51
	s_nop 0
	global_load_lds_dwordx4 v[206:207], off
	v_lshl_add_u64 v[206:207], v[224:225], 0, s[6:7]
	s_mov_b32 m0, s52
	s_nop 0
	global_load_lds_dwordx4 v[206:207], off
	s_waitcnt vmcnt(6) lgkmcnt(0)
	s_barrier
	s_setprio 1
	v_mfma_f32_16x16x32_bf16 v[60:63], v[144:147], v[182:185], v[60:63]
	v_mfma_f32_16x16x32_bf16 v[52:55], v[158:161], v[182:185], v[52:55]
	v_mfma_f32_16x16x32_bf16 v[44:47], v[144:147], v[190:193], v[44:47]
	v_mfma_f32_16x16x32_bf16 v[36:39], v[158:161], v[190:193], v[36:39]
	v_mfma_f32_16x16x32_bf16 v[28:31], v[144:147], v[198:201], v[28:31]
	v_mfma_f32_16x16x32_bf16 v[20:23], v[158:161], v[198:201], v[20:23]
	v_mfma_f32_16x16x32_bf16 v[12:15], v[144:147], v[212:215], v[12:15]
	v_mfma_f32_16x16x32_bf16 v[4:7], v[158:161], v[212:215], v[4:7]
	v_mfma_f32_16x16x32_bf16 v[60:63], v[154:157], v[186:189], v[60:63]
	v_mfma_f32_16x16x32_bf16 v[52:55], v[162:165], v[186:189], v[52:55]
	v_mfma_f32_16x16x32_bf16 v[44:47], v[154:157], v[194:197], v[44:47]
	v_mfma_f32_16x16x32_bf16 v[36:39], v[162:165], v[194:197], v[36:39]
	v_mfma_f32_16x16x32_bf16 v[28:31], v[154:157], v[202:205], v[28:31]
	v_mfma_f32_16x16x32_bf16 v[20:23], v[162:165], v[202:205], v[20:23]
	v_mfma_f32_16x16x32_bf16 v[12:15], v[154:157], v[216:219], v[12:15]
	v_mfma_f32_16x16x32_bf16 v[4:7], v[162:165], v[216:219], v[4:7]
	v_mfma_f32_16x16x32_bf16 v[56:59], v[166:169], v[182:185], v[56:59]
	v_mfma_f32_16x16x32_bf16 v[48:51], v[174:177], v[182:185], v[48:51]
	v_mfma_f32_16x16x32_bf16 v[40:43], v[166:169], v[190:193], v[40:43]
	v_mfma_f32_16x16x32_bf16 v[32:35], v[174:177], v[190:193], v[32:35]
	v_mfma_f32_16x16x32_bf16 v[24:27], v[166:169], v[198:201], v[24:27]
	v_mfma_f32_16x16x32_bf16 v[16:19], v[174:177], v[198:201], v[16:19]
	v_mfma_f32_16x16x32_bf16 v[8:11], v[166:169], v[212:215], v[8:11]
	v_mfma_f32_16x16x32_bf16 v[0:3], v[174:177], v[212:215], v[0:3]
	v_mfma_f32_16x16x32_bf16 v[56:59], v[170:173], v[186:189], v[56:59]
	v_mfma_f32_16x16x32_bf16 v[48:51], v[178:181], v[186:189], v[48:51]
	v_mfma_f32_16x16x32_bf16 v[40:43], v[170:173], v[194:197], v[40:43]
	v_mfma_f32_16x16x32_bf16 v[32:35], v[178:181], v[194:197], v[32:35]
	v_mfma_f32_16x16x32_bf16 v[24:27], v[170:173], v[202:205], v[24:27]
	v_mfma_f32_16x16x32_bf16 v[16:19], v[178:181], v[202:205], v[16:19]
	v_mfma_f32_16x16x32_bf16 v[8:11], v[170:173], v[216:219], v[8:11]
	v_mfma_f32_16x16x32_bf16 v[0:3], v[178:181], v[216:219], v[0:3]
	s_setprio 0
	s_barrier
	s_add_i32 s68, s68, 2
	s_add_u32 s38, s38, 0x100
	s_addc_u32 s39, s39, 0
	s_add_u32 s67, s67, 0x100
	s_addc_u32 s33, s33, 0
	s_cmp_gt_u32 s68, 13
	s_cbranch_scc0 .LBB0_639
	s_and_b64 vcc, exec, s[8:9]
	s_cbranch_vccz .LBB0_642
	s_barrier

.LBB0_722:
	ds_read_b128 v[96:99], v185
	ds_read_b128 v[100:103], v185 offset:1024
	ds_read_b128 v[104:107], v185 offset:2048
	ds_read_b128 v[108:111], v185 offset:3072
	ds_read_b128 v[156:159], v186
	ds_read_b128 v[160:163], v186 offset:1024
	ds_read_b128 v[164:167], v186 offset:2048
	ds_read_b128 v[168:171], v186 offset:3072
	s_add_u32 s28, s26, 0x100
	s_addc_u32 s29, s27, 0
	s_cmp_eq_u32 s57, 40
	s_cselect_b32 s37, s7, s29
	s_cselect_b32 s36, s6, s28
	s_cselect_b32 s35, s23, s56
	s_cselect_b32 s34, s22, s55
	v_lshl_add_u64 v[180:181], s[26:27], 0, v[148:149]
	s_add_i32 m0, s15, 0xc000
	ds_read_b128 v[172:175], v187
	ds_read_b128 v[176:179], v187 offset:1024
	ds_read_b128 v[190:193], v187 offset:2048
	ds_read_b128 v[194:197], v187 offset:3072
	ds_read_b128 v[198:201], v187 offset:4096
	ds_read_b128 v[202:205], v187 offset:5120
	ds_read_b128 v[206:209], v187 offset:6144
	ds_read_b128 v[212:215], v187 offset:7168
	global_load_lds_dwordx4 v[180:181], off
	v_lshl_add_u64 v[180:181], s[26:27], 0, v[150:151]
	s_add_i32 m0, s15, 0xe000
	s_nop 0
	global_load_lds_dwordx4 v[180:181], off
	s_waitcnt vmcnt(8) lgkmcnt(0)
	s_barrier
	s_setprio 1
	v_mfma_f32_16x16x32_bf16 v[140:143], v[96:99], v[172:175], v[140:143]
	v_mfma_f32_16x16x32_bf16 v[136:139], v[104:107], v[172:175], v[136:139]
	v_mfma_f32_16x16x32_bf16 v[124:127], v[96:99], v[190:193], v[124:127]
	v_mfma_f32_16x16x32_bf16 v[120:123], v[104:107], v[190:193], v[120:123]
	v_mfma_f32_16x16x32_bf16 v[92:95], v[96:99], v[198:201], v[92:95]
	v_mfma_f32_16x16x32_bf16 v[88:91], v[104:107], v[198:201], v[88:91]
	v_mfma_f32_16x16x32_bf16 v[76:79], v[96:99], v[206:209], v[76:79]
	v_mfma_f32_16x16x32_bf16 v[72:75], v[104:107], v[206:209], v[72:75]
	v_mfma_f32_16x16x32_bf16 v[140:143], v[100:103], v[176:179], v[140:143]
	v_mfma_f32_16x16x32_bf16 v[136:139], v[108:111], v[176:179], v[136:139]
	v_mfma_f32_16x16x32_bf16 v[124:127], v[100:103], v[194:197], v[124:127]
	v_mfma_f32_16x16x32_bf16 v[120:123], v[108:111], v[194:197], v[120:123]
	v_mfma_f32_16x16x32_bf16 v[92:95], v[100:103], v[202:205], v[92:95]
	v_mfma_f32_16x16x32_bf16 v[88:91], v[108:111], v[202:205], v[88:91]
	v_mfma_f32_16x16x32_bf16 v[76:79], v[100:103], v[212:215], v[76:79]
	v_mfma_f32_16x16x32_bf16 v[72:75], v[108:111], v[212:215], v[72:75]
	v_mfma_f32_16x16x32_bf16 v[132:135], v[156:159], v[172:175], v[132:135]
	v_mfma_f32_16x16x32_bf16 v[128:131], v[164:167], v[172:175], v[128:131]
	v_mfma_f32_16x16x32_bf16 v[116:119], v[156:159], v[190:193], v[116:119]
	v_mfma_f32_16x16x32_bf16 v[112:115], v[164:167], v[190:193], v[112:115]
	v_mfma_f32_16x16x32_bf16 v[84:87], v[156:159], v[198:201], v[84:87]
	v_mfma_f32_16x16x32_bf16 v[80:83], v[164:167], v[198:201], v[80:83]
	v_mfma_f32_16x16x32_bf16 v[68:71], v[156:159], v[206:209], v[68:71]
	v_mfma_f32_16x16x32_bf16 v[64:67], v[164:167], v[206:209], v[64:67]
	v_mfma_f32_16x16x32_bf16 v[132:135], v[160:163], v[176:179], v[132:135]
	v_mfma_f32_16x16x32_bf16 v[128:131], v[168:171], v[176:179], v[128:131]
	v_mfma_f32_16x16x32_bf16 v[116:119], v[160:163], v[194:197], v[116:119]
	v_mfma_f32_16x16x32_bf16 v[112:115], v[168:171], v[194:197], v[112:115]
	v_mfma_f32_16x16x32_bf16 v[84:87], v[160:163], v[202:205], v[84:87]
	v_mfma_f32_16x16x32_bf16 v[80:83], v[168:171], v[202:205], v[80:83]
	v_mfma_f32_16x16x32_bf16 v[68:71], v[160:163], v[212:215], v[68:71]
	v_mfma_f32_16x16x32_bf16 v[64:67], v[168:171], v[212:215], v[64:67]
	s_setprio 0
	s_barrier
	s_add_i32 s26, s49, s3
	v_lshl_add_u64 v[180:181], s[34:35], 0, v[144:145]
	s_mov_b32 m0, s26
	ds_read_b128 v[172:175], v187 offset:16384
	ds_read_b128 v[176:179], v187 offset:17408
	ds_read_b128 v[190:193], v187 offset:18432
	ds_read_b128 v[194:197], v187 offset:19456
	ds_read_b128 v[198:201], v187 offset:20480
	ds_read_b128 v[202:205], v187 offset:21504
	ds_read_b128 v[206:209], v187 offset:22528
	ds_read_b128 v[212:215], v187 offset:23552
	global_load_lds_dwordx4 v[180:181], off
	s_add_i32 m0, s26, 0x2000
	s_add_u32 s26, s34, 0xb0000
	v_lshl_add_u64 v[216:217], s[34:35], 0, v[146:147]
	s_addc_u32 s27, s35, 0
	s_add_i32 s58, s50, s3
	global_load_lds_dwordx4 v[216:217], off
	v_lshl_add_u64 v[218:219], s[26:27], 0, v[144:145]
	s_mov_b32 m0, s58
	v_lshl_add_u64 v[220:221], s[36:37], 0, v[146:147]
	global_load_lds_dwordx4 v[218:219], off
	v_lshl_add_u64 v[218:219], s[26:27], 0, v[146:147]
	s_add_i32 m0, s58, 0x2000
	s_nop 0
	global_load_lds_dwordx4 v[218:219], off
	s_waitcnt vmcnt(6) lgkmcnt(0)
	s_barrier
	s_setprio 1
	v_mfma_f32_16x16x32_bf16 v[60:63], v[96:99], v[172:175], v[60:63]
	v_mfma_f32_16x16x32_bf16 v[56:59], v[104:107], v[172:175], v[56:59]
	v_mfma_f32_16x16x32_bf16 v[44:47], v[96:99], v[190:193], v[44:47]
	v_mfma_f32_16x16x32_bf16 v[40:43], v[104:107], v[190:193], v[40:43]
	v_mfma_f32_16x16x32_bf16 v[28:31], v[96:99], v[198:201], v[28:31]
	v_mfma_f32_16x16x32_bf16 v[24:27], v[104:107], v[198:201], v[24:27]
	v_mfma_f32_16x16x32_bf16 v[12:15], v[96:99], v[206:209], v[12:15]
	v_mfma_f32_16x16x32_bf16 v[8:11], v[104:107], v[206:209], v[8:11]
	v_mfma_f32_16x16x32_bf16 v[60:63], v[100:103], v[176:179], v[60:63]
	v_mfma_f32_16x16x32_bf16 v[56:59], v[108:111], v[176:179], v[56:59]
	v_mfma_f32_16x16x32_bf16 v[44:47], v[100:103], v[194:197], v[44:47]
	v_mfma_f32_16x16x32_bf16 v[40:43], v[108:111], v[194:197], v[40:43]
	v_mfma_f32_16x16x32_bf16 v[28:31], v[100:103], v[202:205], v[28:31]
	v_mfma_f32_16x16x32_bf16 v[24:27], v[108:111], v[202:205], v[24:27]
	v_mfma_f32_16x16x32_bf16 v[12:15], v[100:103], v[212:215], v[12:15]
	v_mfma_f32_16x16x32_bf16 v[8:11], v[108:111], v[212:215], v[8:11]
	v_mfma_f32_16x16x32_bf16 v[52:55], v[156:159], v[172:175], v[52:55]
	v_mfma_f32_16x16x32_bf16 v[48:51], v[164:167], v[172:175], v[48:51]
	v_mfma_f32_16x16x32_bf16 v[36:39], v[156:159], v[190:193], v[36:39]
	v_mfma_f32_16x16x32_bf16 v[32:35], v[164:167], v[190:193], v[32:35]
	v_mfma_f32_16x16x32_bf16 v[20:23], v[156:159], v[198:201], v[20:23]
	v_mfma_f32_16x16x32_bf16 v[16:19], v[164:167], v[198:201], v[16:19]
	v_mfma_f32_16x16x32_bf16 v[4:7], v[156:159], v[206:209], v[4:7]
	v_mfma_f32_16x16x32_bf16 v[0:3], v[164:167], v[206:209], v[0:3]
	v_mfma_f32_16x16x32_bf16 v[52:55], v[160:163], v[176:179], v[52:55]
	v_mfma_f32_16x16x32_bf16 v[48:51], v[168:171], v[176:179], v[48:51]
	v_mfma_f32_16x16x32_bf16 v[36:39], v[160:163], v[194:197], v[36:39]
	v_mfma_f32_16x16x32_bf16 v[32:35], v[168:171], v[194:197], v[32:35]
	v_mfma_f32_16x16x32_bf16 v[20:23], v[160:163], v[202:205], v[20:23]
	v_mfma_f32_16x16x32_bf16 v[16:19], v[168:171], v[202:205], v[16:19]
	v_mfma_f32_16x16x32_bf16 v[4:7], v[160:163], v[212:215], v[4:7]
	v_mfma_f32_16x16x32_bf16 v[0:3], v[168:171], v[212:215], v[0:3]
	s_setprio 0
	s_barrier
	s_add_i32 s58, 0, 0x18000
	s_add_i32 s59, 0, 0x1c000
	v_add_u32_e32 v108, s58, v183
	v_add_u32_e32 v168, s59, v183
	ds_read_b128 v[96:99], v108
	ds_read_b128 v[100:103], v108 offset:1024
	ds_read_b128 v[104:107], v108 offset:2048
	ds_read_b128 v[108:111], v108 offset:3072
	ds_read_b128 v[156:159], v168
	ds_read_b128 v[160:163], v168 offset:1024
	ds_read_b128 v[164:167], v168 offset:2048
	ds_read_b128 v[168:171], v168 offset:3072
	v_lshl_add_u64 v[218:219], s[36:37], 0, v[144:145]
	s_mov_b32 m0, s15
	s_nop 0
	global_load_lds_dwordx4 v[218:219], off
	s_mov_b32 m0, s33
	s_nop 0
	global_load_lds_dwordx4 v[220:221], off
	s_add_u32 s26, s36, 0xb0000
	s_addc_u32 s27, s37, 0
	s_mov_b32 m0, s38
	v_lshl_add_u64 v[222:223], s[26:27], 0, v[144:145]
	ds_read_b128 v[172:175], v187 offset:32768
	ds_read_b128 v[176:179], v187 offset:33792
	ds_read_b128 v[190:193], v187 offset:34816
	ds_read_b128 v[194:197], v187 offset:35840
	ds_read_b128 v[198:201], v187 offset:36864
	ds_read_b128 v[202:205], v187 offset:37888
	ds_read_b128 v[206:209], v187 offset:38912
	ds_read_b128 v[212:215], v187 offset:39936
	global_load_lds_dwordx4 v[222:223], off
	v_lshl_add_u64 v[222:223], s[26:27], 0, v[146:147]
	s_mov_b32 m0, s39
	s_nop 0
	global_load_lds_dwordx4 v[222:223], off
	s_waitcnt vmcnt(8) lgkmcnt(0)
	s_barrier
	s_setprio 1
	v_mfma_f32_16x16x32_bf16 v[140:143], v[96:99], v[172:175], v[140:143]
	v_mfma_f32_16x16x32_bf16 v[136:139], v[104:107], v[172:175], v[136:139]
	v_mfma_f32_16x16x32_bf16 v[124:127], v[96:99], v[190:193], v[124:127]
	v_mfma_f32_16x16x32_bf16 v[120:123], v[104:107], v[190:193], v[120:123]
	v_mfma_f32_16x16x32_bf16 v[92:95], v[96:99], v[198:201], v[92:95]
	v_mfma_f32_16x16x32_bf16 v[88:91], v[104:107], v[198:201], v[88:91]
	v_mfma_f32_16x16x32_bf16 v[76:79], v[96:99], v[206:209], v[76:79]
	v_mfma_f32_16x16x32_bf16 v[72:75], v[104:107], v[206:209], v[72:75]
	v_mfma_f32_16x16x32_bf16 v[140:143], v[100:103], v[176:179], v[140:143]
	v_mfma_f32_16x16x32_bf16 v[136:139], v[108:111], v[176:179], v[136:139]
	v_mfma_f32_16x16x32_bf16 v[124:127], v[100:103], v[194:197], v[124:127]
	v_mfma_f32_16x16x32_bf16 v[120:123], v[108:111], v[194:197], v[120:123]
	v_mfma_f32_16x16x32_bf16 v[92:95], v[100:103], v[202:205], v[92:95]
	v_mfma_f32_16x16x32_bf16 v[88:91], v[108:111], v[202:205], v[88:91]
	v_mfma_f32_16x16x32_bf16 v[76:79], v[100:103], v[212:215], v[76:79]
	v_mfma_f32_16x16x32_bf16 v[72:75], v[108:111], v[212:215], v[72:75]
	v_mfma_f32_16x16x32_bf16 v[132:135], v[156:159], v[172:175], v[132:135]
	v_mfma_f32_16x16x32_bf16 v[128:131], v[164:167], v[172:175], v[128:131]
	v_mfma_f32_16x16x32_bf16 v[116:119], v[156:159], v[190:193], v[116:119]
	v_mfma_f32_16x16x32_bf16 v[112:115], v[164:167], v[190:193], v[112:115]
	v_mfma_f32_16x16x32_bf16 v[84:87], v[156:159], v[198:201], v[84:87]
	v_mfma_f32_16x16x32_bf16 v[80:83], v[164:167], v[198:201], v[80:83]
	v_mfma_f32_16x16x32_bf16 v[68:71], v[156:159], v[206:209], v[68:71]
	v_mfma_f32_16x16x32_bf16 v[64:67], v[164:167], v[206:209], v[64:67]
	v_mfma_f32_16x16x32_bf16 v[132:135], v[160:163], v[176:179], v[132:135]
	v_mfma_f32_16x16x32_bf16 v[128:131], v[168:171], v[176:179], v[128:131]
	v_mfma_f32_16x16x32_bf16 v[116:119], v[160:163], v[194:197], v[116:119]
	v_mfma_f32_16x16x32_bf16 v[112:115], v[168:171], v[194:197], v[112:115]
	v_mfma_f32_16x16x32_bf16 v[84:87], v[160:163], v[202:205], v[84:87]
	v_mfma_f32_16x16x32_bf16 v[80:83], v[168:171], v[202:205], v[80:83]
	v_mfma_f32_16x16x32_bf16 v[68:71], v[160:163], v[212:215], v[68:71]
	v_mfma_f32_16x16x32_bf16 v[64:67], v[168:171], v[212:215], v[64:67]
	s_setprio 0
	s_barrier
	s_add_i32 s26, s58, s3
	v_lshl_add_u64 v[180:181], v[180:181], 0, s[16:17]
	s_mov_b32 m0, s26
	ds_read_b128 v[172:175], v187 offset:49152
	ds_read_b128 v[176:179], v187 offset:50176
	ds_read_b128 v[190:193], v187 offset:51200
	ds_read_b128 v[194:197], v187 offset:52224
	ds_read_b128 v[198:201], v187 offset:53248
	ds_read_b128 v[202:205], v187 offset:54272
	ds_read_b128 v[206:209], v187 offset:55296
	ds_read_b128 v[212:215], v187 offset:56320
	global_load_lds_dwordx4 v[180:181], off
	s_add_i32 m0, s26, 0x2000
	s_add_u32 s26, s34, 0xb0080
	v_lshl_add_u64 v[180:181], v[216:217], 0, s[16:17]
	s_addc_u32 s27, s35, 0
	s_add_i32 s34, s59, s3
	global_load_lds_dwordx4 v[180:181], off
	v_lshl_add_u64 v[180:181], s[26:27], 0, v[144:145]
	s_mov_b32 m0, s34
	s_nop 0
	global_load_lds_dwordx4 v[180:181], off
	v_lshl_add_u64 v[180:181], s[26:27], 0, v[146:147]
	s_add_i32 m0, s34, 0x2000
	s_nop 0
	global_load_lds_dwordx4 v[180:181], off
	v_lshl_add_u64 v[180:181], v[218:219], 0, s[16:17]
	s_mov_b32 m0, s45
	s_nop 0
	global_load_lds_dwordx4 v[180:181], off
	v_lshl_add_u64 v[180:181], v[220:221], 0, s[16:17]
	s_mov_b32 m0, s46
	s_nop 0
	global_load_lds_dwordx4 v[180:181], off
	s_waitcnt vmcnt(6) lgkmcnt(0)
	s_barrier
	s_setprio 1
	v_mfma_f32_16x16x32_bf16 v[60:63], v[96:99], v[172:175], v[60:63]
	v_mfma_f32_16x16x32_bf16 v[56:59], v[104:107], v[172:175], v[56:59]
	v_mfma_f32_16x16x32_bf16 v[44:47], v[96:99], v[190:193], v[44:47]
	v_mfma_f32_16x16x32_bf16 v[40:43], v[104:107], v[190:193], v[40:43]
	v_mfma_f32_16x16x32_bf16 v[28:31], v[96:99], v[198:201], v[28:31]
	v_mfma_f32_16x16x32_bf16 v[24:27], v[104:107], v[198:201], v[24:27]
	v_mfma_f32_16x16x32_bf16 v[12:15], v[96:99], v[206:209], v[12:15]
	v_mfma_f32_16x16x32_bf16 v[8:11], v[104:107], v[206:209], v[8:11]
	v_mfma_f32_16x16x32_bf16 v[60:63], v[100:103], v[176:179], v[60:63]
	v_mfma_f32_16x16x32_bf16 v[56:59], v[108:111], v[176:179], v[56:59]
	v_mfma_f32_16x16x32_bf16 v[44:47], v[100:103], v[194:197], v[44:47]
	v_mfma_f32_16x16x32_bf16 v[40:43], v[108:111], v[194:197], v[40:43]
	v_mfma_f32_16x16x32_bf16 v[28:31], v[100:103], v[202:205], v[28:31]
	v_mfma_f32_16x16x32_bf16 v[24:27], v[108:111], v[202:205], v[24:27]
	v_mfma_f32_16x16x32_bf16 v[12:15], v[100:103], v[212:215], v[12:15]
	v_mfma_f32_16x16x32_bf16 v[8:11], v[108:111], v[212:215], v[8:11]
	v_mfma_f32_16x16x32_bf16 v[52:55], v[156:159], v[172:175], v[52:55]
	v_mfma_f32_16x16x32_bf16 v[48:51], v[164:167], v[172:175], v[48:51]
	v_mfma_f32_16x16x32_bf16 v[36:39], v[156:159], v[190:193], v[36:39]
	v_mfma_f32_16x16x32_bf16 v[32:35], v[164:167], v[190:193], v[32:35]
	v_mfma_f32_16x16x32_bf16 v[20:23], v[156:159], v[198:201], v[20:23]
	v_mfma_f32_16x16x32_bf16 v[16:19], v[164:167], v[198:201], v[16:19]
	v_mfma_f32_16x16x32_bf16 v[4:7], v[156:159], v[206:209], v[4:7]
	v_mfma_f32_16x16x32_bf16 v[0:3], v[164:167], v[206:209], v[0:3]
	v_mfma_f32_16x16x32_bf16 v[52:55], v[160:163], v[176:179], v[52:55]
	v_mfma_f32_16x16x32_bf16 v[48:51], v[168:171], v[176:179], v[48:51]
	v_mfma_f32_16x16x32_bf16 v[36:39], v[160:163], v[194:197], v[36:39]
	v_mfma_f32_16x16x32_bf16 v[32:35], v[168:171], v[194:197], v[32:35]
	v_mfma_f32_16x16x32_bf16 v[20:23], v[160:163], v[202:205], v[20:23]
	v_mfma_f32_16x16x32_bf16 v[16:19], v[168:171], v[202:205], v[16:19]
	v_mfma_f32_16x16x32_bf16 v[4:7], v[160:163], v[212:215], v[4:7]
	v_mfma_f32_16x16x32_bf16 v[0:3], v[168:171], v[212:215], v[0:3]
	s_setprio 0
	s_barrier
	s_add_i32 s57, s57, 2
	s_add_u32 s55, s55, 0x100
	s_addc_u32 s56, s56, 0
	s_cmp_gt_u32 s57, 41
	s_mov_b64 s[26:27], s[28:29]
	s_cbranch_scc0 .LBB0_722
	s_and_b64 vcc, exec, s[20:21]
	s_cbranch_vccz .LBB0_725
	s_barrier
